# weight-conversion item loops (P0 prologue ids 0,1; attention-tail ids 2,3,6,7): 8 serialized load+wait round trips per item replaced by issue-all / wait-once; plus P1 DMA saddr form
# speedup vs baseline: 1.0360x; 1.0216x over previous
.LBB0_19:
.Lcv_p0a_tr:
	s_waitcnt lgkmcnt(0)
	v_add_u32_e32 v14, s27, v8
	ds_read2_b32 v[2:3], v23 offset1:36
	s_ashr_i32 s21, s20, 31
	v_ashrrev_i32_e32 v15, 31, v14
	s_waitcnt lgkmcnt(0)
	v_cvt_pk_bf16_f32 v2, v2, v3
	ds_read2_b32 v[4:5], v23 offset0:72 offset1:108
	v_lshl_add_u64 v[26:27], s[20:21], 1, v[12:13]
	v_lshlrev_b64 v[28:29], 11, v[14:15]
	s_waitcnt lgkmcnt(0)
	v_cvt_pk_bf16_f32 v3, v4, v5
	ds_read2_b32 v[4:5], v23 offset0:144 offset1:180
	v_lshl_add_u64 v[28:29], v[26:27], 0, v[28:29]
	s_waitcnt lgkmcnt(0)
	v_cvt_pk_bf16_f32 v4, v4, v5
	ds_read2_b32 v[6:7], v23 offset0:216 offset1:252
	s_waitcnt lgkmcnt(0)
	v_cvt_pk_bf16_f32 v5, v6, v7
	global_store_dwordx4 v[28:29], v[2:5], off
	v_add_u32_e32 v28, 8, v14
	v_ashrrev_i32_e32 v29, 31, v28
	ds_read2_b32 v[6:7], v23 offset0:8 offset1:44
	s_waitcnt lgkmcnt(0)
	v_cvt_pk_bf16_f32 v2, v6, v7
	ds_read2_b32 v[4:5], v23 offset0:80 offset1:116
	v_lshlrev_b64 v[28:29], 11, v[28:29]
	s_waitcnt lgkmcnt(0)
	v_cvt_pk_bf16_f32 v3, v4, v5
	ds_read2_b32 v[4:5], v23 offset0:152 offset1:188
	v_add_u32_e32 v10, 0x200, v23
	v_lshl_add_u64 v[28:29], v[26:27], 0, v[28:29]
	s_waitcnt lgkmcnt(0)
	v_cvt_pk_bf16_f32 v4, v4, v5
	ds_read2_b32 v[6:7], v10 offset0:96 offset1:132
	s_waitcnt lgkmcnt(0)
	v_cvt_pk_bf16_f32 v5, v6, v7
	global_store_dwordx4 v[28:29], v[2:5], off
	v_add_u32_e32 v28, 16, v14
	ds_read2_b32 v[6:7], v23 offset0:16 offset1:52
	s_waitcnt lgkmcnt(0)
	v_cvt_pk_bf16_f32 v2, v6, v7
	ds_read2_b32 v[4:5], v23 offset0:88 offset1:124
	v_ashrrev_i32_e32 v29, 31, v28
	s_waitcnt lgkmcnt(0)
	v_cvt_pk_bf16_f32 v3, v4, v5
	ds_read2_b32 v[4:5], v23 offset0:160 offset1:196
	v_lshlrev_b64 v[28:29], 11, v[28:29]
	v_add_u32_e32 v14, 24, v14
	s_waitcnt lgkmcnt(0)
	v_cvt_pk_bf16_f32 v4, v4, v5
	ds_read2_b32 v[6:7], v10 offset0:104 offset1:140
	s_waitcnt lgkmcnt(0)
	v_cvt_pk_bf16_f32 v5, v6, v7
	v_lshl_add_u64 v[28:29], v[26:27], 0, v[28:29]
	v_ashrrev_i32_e32 v15, 31, v14
	ds_read2_b32 v[6:7], v23 offset0:24 offset1:60
	global_store_dwordx4 v[28:29], v[2:5], off
	v_lshlrev_b64 v[14:15], 11, v[14:15]
	v_lshl_add_u64 v[14:15], v[26:27], 0, v[14:15]
	s_waitcnt lgkmcnt(0)
	v_cvt_pk_bf16_f32 v2, v6, v7
	ds_read2_b32 v[4:5], v23 offset0:96 offset1:132
	s_waitcnt lgkmcnt(0)
	v_cvt_pk_bf16_f32 v3, v4, v5
	ds_read2_b32 v[4:5], v23 offset0:168 offset1:204
	s_waitcnt lgkmcnt(0)
	v_cvt_pk_bf16_f32 v4, v4, v5
	ds_read2_b32 v[6:7], v10 offset0:112 offset1:148
	s_waitcnt lgkmcnt(0)
	v_cvt_pk_bf16_f32 v5, v6, v7
	global_store_dwordx4 v[14:15], v[2:5], off
	s_waitcnt lgkmcnt(0)
	s_add_i32 s26, s26, s28
	s_add_i32 s1, s1, s2
	s_add_i32 s12, s12, s13
	s_cmpk_lt_i32 s26, 0xb00
	s_cbranch_scc0 .LBB0_44
.LBB0_20:
	s_mul_hi_i32 s20, s26, 0x2e8ba2e9
	s_lshr_b32 s21, s20, 31
	s_ashr_i32 s20, s20, 5
	s_add_i32 s21, s20, s21
	s_mul_i32 s22, s21, 0xffffea00
	s_lshl_b32 s20, s21, 6
	s_add_i32 s27, s1, s22
	s_bitcmp0_b32 s26, 2
	s_mulk_i32 s21, 0xf500
	s_cselect_b32 s23, s11, s19
	s_cselect_b32 s22, s10, s18
	s_add_i32 s21, s12, s21
	s_and_b32 s24, s21, 0xffffff80
	s_ashr_i32 s25, s24, 31
	s_lshl_b64 s[24:25], s[24:25], 2
	s_add_u32 s24, s22, s24
	s_addc_u32 s25, s23, s25
	s_and_b32 s21, s27, 0x60
	v_or_b32_e32 v2, s21, v1
	s_cmp_lg_u64 s[22:23], 0
	v_or_b32_e32 v6, s20, v8
	v_lshlrev_b32_e32 v10, 2, v2
	s_cselect_b64 s[22:23], -1, 0
	v_lshl_add_u64 v[14:15], s[24:25], 0, v[10:11]
	v_mov_b32_e32 v80, v6
	v_cmp_gt_i32_e32 vcc, s14, v80
	s_and_b64 s[98:99], s[22:23], vcc
	v_mov_b32_e32 v96, 0
	v_mov_b32_e32 v97, 0
	v_mov_b32_e32 v98, 0
	v_mov_b32_e32 v99, 0
	v_mov_b32_e32 v160, 1.0
	s_and_saveexec_b64 s[100:101], s[98:99]
	v_mad_i64_i32 v[128:129], s[98:99], v80, s15, v[14:15]
	global_load_dwordx4 v[96:99], v[128:129], off nt
	s_and_b64 vcc, exec, s[4:5]
	s_cbranch_vccnz .Lcv_p0a_ng0
	v_ashrrev_i32_e32 v81, 31, v80
	v_lshl_add_u64 v[144:145], v[80:81], 2, s[8:9]
	global_load_dword v160, v[144:145], off
.Lcv_p0a_ng0:
	s_or_b64 exec, exec, s[100:101]
	v_or_b32_e32 v82, s20, v16
	v_cmp_gt_i32_e32 vcc, s14, v82
	s_and_b64 s[98:99], s[22:23], vcc
	v_mov_b32_e32 v100, 0
	v_mov_b32_e32 v101, 0
	v_mov_b32_e32 v102, 0
	v_mov_b32_e32 v103, 0
	v_mov_b32_e32 v161, 1.0
	s_and_saveexec_b64 s[100:101], s[98:99]
	v_mad_i64_i32 v[130:131], s[98:99], v82, s15, v[14:15]
	global_load_dwordx4 v[100:103], v[130:131], off nt
	s_and_b64 vcc, exec, s[4:5]
	s_cbranch_vccnz .Lcv_p0a_ng1
	v_ashrrev_i32_e32 v83, 31, v82
	v_lshl_add_u64 v[146:147], v[82:83], 2, s[8:9]
	global_load_dword v161, v[146:147], off
.Lcv_p0a_ng1:
	s_or_b64 exec, exec, s[100:101]
	v_or_b32_e32 v84, s20, v17
	v_cmp_gt_i32_e32 vcc, s14, v84
	s_and_b64 s[98:99], s[22:23], vcc
	v_mov_b32_e32 v104, 0
	v_mov_b32_e32 v105, 0
	v_mov_b32_e32 v106, 0
	v_mov_b32_e32 v107, 0
	v_mov_b32_e32 v162, 1.0
	s_and_saveexec_b64 s[100:101], s[98:99]
	v_mad_i64_i32 v[132:133], s[98:99], v84, s15, v[14:15]
	global_load_dwordx4 v[104:107], v[132:133], off nt
	s_and_b64 vcc, exec, s[4:5]
	s_cbranch_vccnz .Lcv_p0a_ng2
	v_ashrrev_i32_e32 v85, 31, v84
	v_lshl_add_u64 v[148:149], v[84:85], 2, s[8:9]
	global_load_dword v162, v[148:149], off
.Lcv_p0a_ng2:
	s_or_b64 exec, exec, s[100:101]
	v_or_b32_e32 v86, s20, v18
	v_cmp_gt_i32_e32 vcc, s14, v86
	s_and_b64 s[98:99], s[22:23], vcc
	v_mov_b32_e32 v108, 0
	v_mov_b32_e32 v109, 0
	v_mov_b32_e32 v110, 0
	v_mov_b32_e32 v111, 0
	v_mov_b32_e32 v163, 1.0
	s_and_saveexec_b64 s[100:101], s[98:99]
	v_mad_i64_i32 v[134:135], s[98:99], v86, s15, v[14:15]
	global_load_dwordx4 v[108:111], v[134:135], off nt
	s_and_b64 vcc, exec, s[4:5]
	s_cbranch_vccnz .Lcv_p0a_ng3
	v_ashrrev_i32_e32 v87, 31, v86
	v_lshl_add_u64 v[150:151], v[86:87], 2, s[8:9]
	global_load_dword v163, v[150:151], off
.Lcv_p0a_ng3:
	s_or_b64 exec, exec, s[100:101]
	v_or_b32_e32 v88, s20, v19
	v_cmp_gt_i32_e32 vcc, s14, v88
	s_and_b64 s[98:99], s[22:23], vcc
	v_mov_b32_e32 v112, 0
	v_mov_b32_e32 v113, 0
	v_mov_b32_e32 v114, 0
	v_mov_b32_e32 v115, 0
	v_mov_b32_e32 v164, 1.0
	s_and_saveexec_b64 s[100:101], s[98:99]
	v_mad_i64_i32 v[136:137], s[98:99], v88, s15, v[14:15]
	global_load_dwordx4 v[112:115], v[136:137], off nt
	s_and_b64 vcc, exec, s[4:5]
	s_cbranch_vccnz .Lcv_p0a_ng4
	v_ashrrev_i32_e32 v89, 31, v88
	v_lshl_add_u64 v[152:153], v[88:89], 2, s[8:9]
	global_load_dword v164, v[152:153], off
.Lcv_p0a_ng4:
	s_or_b64 exec, exec, s[100:101]
	v_or_b32_e32 v90, s20, v20
	v_cmp_gt_i32_e32 vcc, s14, v90
	s_and_b64 s[98:99], s[22:23], vcc
	v_mov_b32_e32 v116, 0
	v_mov_b32_e32 v117, 0
	v_mov_b32_e32 v118, 0
	v_mov_b32_e32 v119, 0
	v_mov_b32_e32 v165, 1.0
	s_and_saveexec_b64 s[100:101], s[98:99]
	v_mad_i64_i32 v[138:139], s[98:99], v90, s15, v[14:15]
	global_load_dwordx4 v[116:119], v[138:139], off nt
	s_and_b64 vcc, exec, s[4:5]
	s_cbranch_vccnz .Lcv_p0a_ng5
	v_ashrrev_i32_e32 v91, 31, v90
	v_lshl_add_u64 v[154:155], v[90:91], 2, s[8:9]
	global_load_dword v165, v[154:155], off
.Lcv_p0a_ng5:
	s_or_b64 exec, exec, s[100:101]
	v_or_b32_e32 v92, s20, v21
	v_cmp_gt_i32_e32 vcc, s14, v92
	s_and_b64 s[98:99], s[22:23], vcc
	v_mov_b32_e32 v120, 0
	v_mov_b32_e32 v121, 0
	v_mov_b32_e32 v122, 0
	v_mov_b32_e32 v123, 0
	v_mov_b32_e32 v166, 1.0
	s_and_saveexec_b64 s[100:101], s[98:99]
	v_mad_i64_i32 v[140:141], s[98:99], v92, s15, v[14:15]
	global_load_dwordx4 v[120:123], v[140:141], off nt
	s_and_b64 vcc, exec, s[4:5]
	s_cbranch_vccnz .Lcv_p0a_ng6
	v_ashrrev_i32_e32 v93, 31, v92
	v_lshl_add_u64 v[156:157], v[92:93], 2, s[8:9]
	global_load_dword v166, v[156:157], off
.Lcv_p0a_ng6:
	s_or_b64 exec, exec, s[100:101]
	v_or_b32_e32 v94, s20, v22
	v_cmp_gt_i32_e32 vcc, s14, v94
	s_and_b64 s[98:99], s[22:23], vcc
	v_mov_b32_e32 v124, 0
	v_mov_b32_e32 v125, 0
	v_mov_b32_e32 v126, 0
	v_mov_b32_e32 v127, 0
	v_mov_b32_e32 v167, 1.0
	s_and_saveexec_b64 s[100:101], s[98:99]
	v_mad_i64_i32 v[142:143], s[98:99], v94, s15, v[14:15]
	global_load_dwordx4 v[124:127], v[142:143], off nt
	s_and_b64 vcc, exec, s[4:5]
	s_cbranch_vccnz .Lcv_p0a_ng7
	v_ashrrev_i32_e32 v95, 31, v94
	v_lshl_add_u64 v[158:159], v[94:95], 2, s[8:9]
	global_load_dword v167, v[158:159], off
.Lcv_p0a_ng7:
	s_or_b64 exec, exec, s[100:101]
	s_waitcnt vmcnt(0)
	v_mul_f32_e32 v96, v96, v160
	v_mul_f32_e32 v97, v97, v160
	v_mul_f32_e32 v98, v98, v160
	v_mul_f32_e32 v99, v99, v160
	v_mul_f32_e32 v100, v100, v161
	v_mul_f32_e32 v101, v101, v161
	v_mul_f32_e32 v102, v102, v161
	v_mul_f32_e32 v103, v103, v161
	v_mul_f32_e32 v104, v104, v162
	v_mul_f32_e32 v105, v105, v162
	v_mul_f32_e32 v106, v106, v162
	v_mul_f32_e32 v107, v107, v162
	v_mul_f32_e32 v108, v108, v163
	v_mul_f32_e32 v109, v109, v163
	v_mul_f32_e32 v110, v110, v163
	v_mul_f32_e32 v111, v111, v163
	v_mul_f32_e32 v112, v112, v164
	v_mul_f32_e32 v113, v113, v164
	v_mul_f32_e32 v114, v114, v164
	v_mul_f32_e32 v115, v115, v164
	v_mul_f32_e32 v116, v116, v165
	v_mul_f32_e32 v117, v117, v165
	v_mul_f32_e32 v118, v118, v165
	v_mul_f32_e32 v119, v119, v165
	v_mul_f32_e32 v120, v120, v166
	v_mul_f32_e32 v121, v121, v166
	v_mul_f32_e32 v122, v122, v166
	v_mul_f32_e32 v123, v123, v166
	v_mul_f32_e32 v124, v124, v167
	v_mul_f32_e32 v125, v125, v167
	v_mul_f32_e32 v126, v126, v167
	v_mul_f32_e32 v127, v127, v167
	ds_write_b128 v24, v[96:99]
	ds_write_b128 v24, v[100:103] offset:1152
	ds_write_b128 v24, v[104:107] offset:2304
	ds_write_b128 v24, v[108:111] offset:3456
	ds_write_b128 v24, v[112:115] offset:4608
	ds_write_b128 v24, v[116:119] offset:5760
	ds_write_b128 v24, v[120:123] offset:6912
	ds_write_b128 v24, v[124:127] offset:8064
	s_branch .Lcv_p0a_tr

.LBB0_46:
.Lcv_p0b_tr:
	s_waitcnt lgkmcnt(0)
	v_or_b32_e32 v12, s14, v1
	ds_read2_b32 v[2:3], v22 offset1:36
	s_ashr_i32 s11, s10, 31
	v_mul_lo_u32 v12, v12, s12
	s_waitcnt lgkmcnt(0)
	v_cvt_pk_bf16_f32 v2, v2, v3
	ds_read2_b32 v[4:5], v22 offset0:72 offset1:108
	v_lshl_add_u64 v[10:11], s[10:11], 1, v[8:9]
	v_ashrrev_i32_e32 v13, 31, v12
	s_waitcnt lgkmcnt(0)
	v_cvt_pk_bf16_f32 v3, v4, v5
	ds_read2_b32 v[4:5], v22 offset0:144 offset1:180
	v_lshl_add_u64 v[12:13], v[10:11], 0, v[12:13]
	s_waitcnt lgkmcnt(0)
	v_cvt_pk_bf16_f32 v4, v4, v5
	ds_read2_b32 v[6:7], v22 offset0:216 offset1:252
	s_waitcnt lgkmcnt(0)
	v_cvt_pk_bf16_f32 v5, v6, v7
	global_store_dwordx4 v[12:13], v[2:5], off
	v_or_b32_e32 v12, s14, v15
	v_mul_lo_u32 v12, v12, s12
	ds_read2_b32 v[6:7], v22 offset0:8 offset1:44
	s_waitcnt lgkmcnt(0)
	v_cvt_pk_bf16_f32 v2, v6, v7
	ds_read2_b32 v[4:5], v22 offset0:80 offset1:116
	v_ashrrev_i32_e32 v13, 31, v12
	s_waitcnt lgkmcnt(0)
	v_cvt_pk_bf16_f32 v3, v4, v5
	ds_read2_b32 v[4:5], v22 offset0:152 offset1:188
	v_add_u32_e32 v24, 0x200, v22
	v_lshl_add_u64 v[12:13], v[10:11], 0, v[12:13]
	s_waitcnt lgkmcnt(0)
	v_cvt_pk_bf16_f32 v4, v4, v5
	ds_read2_b32 v[6:7], v24 offset0:96 offset1:132
	s_waitcnt lgkmcnt(0)
	v_cvt_pk_bf16_f32 v5, v6, v7
	global_store_dwordx4 v[12:13], v[2:5], off
	v_or_b32_e32 v12, s14, v16
	v_mul_lo_u32 v12, v12, s12
	ds_read2_b32 v[6:7], v22 offset0:16 offset1:52
	s_waitcnt lgkmcnt(0)
	v_cvt_pk_bf16_f32 v2, v6, v7
	ds_read2_b32 v[4:5], v22 offset0:88 offset1:124
	v_ashrrev_i32_e32 v13, 31, v12
	s_waitcnt lgkmcnt(0)
	v_cvt_pk_bf16_f32 v3, v4, v5
	ds_read2_b32 v[4:5], v22 offset0:160 offset1:196
	v_lshl_add_u64 v[12:13], v[10:11], 0, v[12:13]
	s_waitcnt lgkmcnt(0)
	v_cvt_pk_bf16_f32 v4, v4, v5
	ds_read2_b32 v[6:7], v24 offset0:104 offset1:140
	s_waitcnt lgkmcnt(0)
	v_cvt_pk_bf16_f32 v5, v6, v7
	global_store_dwordx4 v[12:13], v[2:5], off
	v_or_b32_e32 v12, s14, v17
	v_mul_lo_u32 v12, v12, s12
	ds_read2_b32 v[6:7], v22 offset0:24 offset1:60
	s_waitcnt lgkmcnt(0)
	v_cvt_pk_bf16_f32 v2, v6, v7
	ds_read2_b32 v[4:5], v22 offset0:96 offset1:132
	v_ashrrev_i32_e32 v13, 31, v12
	s_waitcnt lgkmcnt(0)
	v_cvt_pk_bf16_f32 v3, v4, v5
	ds_read2_b32 v[4:5], v22 offset0:168 offset1:204
	v_lshl_add_u64 v[10:11], v[10:11], 0, v[12:13]
	s_waitcnt lgkmcnt(0)
	v_cvt_pk_bf16_f32 v4, v4, v5
	ds_read2_b32 v[6:7], v24 offset0:112 offset1:148
	s_waitcnt lgkmcnt(0)
	v_cvt_pk_bf16_f32 v5, v6, v7
	global_store_dwordx4 v[10:11], v[2:5], off
	s_waitcnt lgkmcnt(0)
	s_add_i32 s13, s13, s28
	s_add_i32 s10, s13, 0xb00
	s_cmpk_lt_i32 s10, 0x1080
	s_cbranch_scc0 .LBB0_63
.LBB0_47:
	s_ashr_i32 s10, s13, 31
	s_lshr_b32 s10, s10, 27
	s_add_i32 s10, s13, s10
	s_and_b32 s11, s10, 0x7ffffe0
	s_sub_i32 s11, s13, s11
	s_lshl_b32 s10, s10, 1
	s_andn2_b32 s10, s10, 63
	s_lshl_b32 s14, s11, 5
	v_or_b32_e32 v2, s14, v14
	v_or_b32_e32 v6, s10, v1
	v_ashrrev_i32_e32 v3, 31, v2
	v_lshl_add_u64 v[10:11], v[2:3], 2, s[4:5]
	v_mov_b32_e32 v80, v6
	v_cmp_gt_i32_e32 vcc, s2, v80
	s_and_b64 s[98:99], s[8:9], vcc
	v_mov_b32_e32 v96, 0
	v_mov_b32_e32 v97, 0
	v_mov_b32_e32 v98, 0
	v_mov_b32_e32 v99, 0
	s_and_saveexec_b64 s[100:101], s[98:99]
	v_ashrrev_i32_e32 v81, 31, v80
	v_lshlrev_b64 v[128:129], 12, v[80:81]
	v_lshl_add_u64 v[128:129], v[10:11], 0, v[128:129]
	global_load_dwordx4 v[96:99], v[128:129], off nt
	s_or_b64 exec, exec, s[100:101]
	v_or_b32_e32 v82, s10, v15
	v_cmp_gt_i32_e32 vcc, s2, v82
	s_and_b64 s[98:99], s[8:9], vcc
	v_mov_b32_e32 v100, 0
	v_mov_b32_e32 v101, 0
	v_mov_b32_e32 v102, 0
	v_mov_b32_e32 v103, 0
	s_and_saveexec_b64 s[100:101], s[98:99]
	v_ashrrev_i32_e32 v83, 31, v82
	v_lshlrev_b64 v[130:131], 12, v[82:83]
	v_lshl_add_u64 v[130:131], v[10:11], 0, v[130:131]
	global_load_dwordx4 v[100:103], v[130:131], off nt
	s_or_b64 exec, exec, s[100:101]
	v_or_b32_e32 v84, s10, v16
	v_cmp_gt_i32_e32 vcc, s2, v84
	s_and_b64 s[98:99], s[8:9], vcc
	v_mov_b32_e32 v104, 0
	v_mov_b32_e32 v105, 0
	v_mov_b32_e32 v106, 0
	v_mov_b32_e32 v107, 0
	s_and_saveexec_b64 s[100:101], s[98:99]
	v_ashrrev_i32_e32 v85, 31, v84
	v_lshlrev_b64 v[132:133], 12, v[84:85]
	v_lshl_add_u64 v[132:133], v[10:11], 0, v[132:133]
	global_load_dwordx4 v[104:107], v[132:133], off nt
	s_or_b64 exec, exec, s[100:101]
	v_or_b32_e32 v86, s10, v17
	v_cmp_gt_i32_e32 vcc, s2, v86
	s_and_b64 s[98:99], s[8:9], vcc
	v_mov_b32_e32 v108, 0
	v_mov_b32_e32 v109, 0
	v_mov_b32_e32 v110, 0
	v_mov_b32_e32 v111, 0
	s_and_saveexec_b64 s[100:101], s[98:99]
	v_ashrrev_i32_e32 v87, 31, v86
	v_lshlrev_b64 v[134:135], 12, v[86:87]
	v_lshl_add_u64 v[134:135], v[10:11], 0, v[134:135]
	global_load_dwordx4 v[108:111], v[134:135], off nt
	s_or_b64 exec, exec, s[100:101]
	v_or_b32_e32 v88, s10, v18
	v_cmp_gt_i32_e32 vcc, s2, v88
	s_and_b64 s[98:99], s[8:9], vcc
	v_mov_b32_e32 v112, 0
	v_mov_b32_e32 v113, 0
	v_mov_b32_e32 v114, 0
	v_mov_b32_e32 v115, 0
	s_and_saveexec_b64 s[100:101], s[98:99]
	v_ashrrev_i32_e32 v89, 31, v88
	v_lshlrev_b64 v[136:137], 12, v[88:89]
	v_lshl_add_u64 v[136:137], v[10:11], 0, v[136:137]
	global_load_dwordx4 v[112:115], v[136:137], off nt
	s_or_b64 exec, exec, s[100:101]
	v_or_b32_e32 v90, s10, v19
	v_cmp_gt_i32_e32 vcc, s2, v90
	s_and_b64 s[98:99], s[8:9], vcc
	v_mov_b32_e32 v116, 0
	v_mov_b32_e32 v117, 0
	v_mov_b32_e32 v118, 0
	v_mov_b32_e32 v119, 0
	s_and_saveexec_b64 s[100:101], s[98:99]
	v_ashrrev_i32_e32 v91, 31, v90
	v_lshlrev_b64 v[138:139], 12, v[90:91]
	v_lshl_add_u64 v[138:139], v[10:11], 0, v[138:139]
	global_load_dwordx4 v[116:119], v[138:139], off nt
	s_or_b64 exec, exec, s[100:101]
	v_or_b32_e32 v92, s10, v20
	v_cmp_gt_i32_e32 vcc, s2, v92
	s_and_b64 s[98:99], s[8:9], vcc
	v_mov_b32_e32 v120, 0
	v_mov_b32_e32 v121, 0
	v_mov_b32_e32 v122, 0
	v_mov_b32_e32 v123, 0
	s_and_saveexec_b64 s[100:101], s[98:99]
	v_ashrrev_i32_e32 v93, 31, v92
	v_lshlrev_b64 v[140:141], 12, v[92:93]
	v_lshl_add_u64 v[140:141], v[10:11], 0, v[140:141]
	global_load_dwordx4 v[120:123], v[140:141], off nt
	s_or_b64 exec, exec, s[100:101]
	v_or_b32_e32 v94, s10, v21
	v_cmp_gt_i32_e32 vcc, s2, v94
	s_and_b64 s[98:99], s[8:9], vcc
	v_mov_b32_e32 v124, 0
	v_mov_b32_e32 v125, 0
	v_mov_b32_e32 v126, 0
	v_mov_b32_e32 v127, 0
	s_and_saveexec_b64 s[100:101], s[98:99]
	v_ashrrev_i32_e32 v95, 31, v94
	v_lshlrev_b64 v[142:143], 12, v[94:95]
	v_lshl_add_u64 v[142:143], v[10:11], 0, v[142:143]
	global_load_dwordx4 v[124:127], v[142:143], off nt
	s_or_b64 exec, exec, s[100:101]
	s_waitcnt vmcnt(0)
	ds_write_b128 v23, v[96:99]
	ds_write_b128 v23, v[100:103] offset:1152
	ds_write_b128 v23, v[104:107] offset:2304
	ds_write_b128 v23, v[108:111] offset:3456
	ds_write_b128 v23, v[112:115] offset:4608
	ds_write_b128 v23, v[116:119] offset:5760
	ds_write_b128 v23, v[120:123] offset:6912
	ds_write_b128 v23, v[124:127] offset:8064
	s_branch .Lcv_p0b_tr

.LBB0_332:
	v_add_u32_e32 v146, s53, v225
	v_add_u32_e32 v162, s54, v225
	ds_read_b128 v[134:137], v146
	ds_read_b128 v[138:141], v146 offset:1024
	ds_read_b128 v[142:145], v146 offset:2048
	ds_read_b128 v[146:149], v146 offset:3072
	ds_read_b128 v[150:153], v162
	ds_read_b128 v[154:157], v162 offset:1024
	ds_read_b128 v[158:161], v162 offset:2048
	ds_read_b128 v[162:165], v162 offset:3072
	s_add_u32 s48, s28, 0xfffc0080
	s_addc_u32 s49, s29, -1
	s_and_b64 s[46:47], s[30:31], exec
	s_cselect_b32 s49, s23, s49
	s_cselect_b32 s48, s56, s48
	s_cselect_b32 s47, s57, s60
	s_cselect_b32 s46, s58, s59
	s_add_i32 m0, s40, 0xc000
	ds_read_b128 v[166:169], v229
	ds_read_b128 v[170:173], v229 offset:1024
	ds_read_b128 v[174:177], v229 offset:2048
	ds_read_b128 v[178:181], v229 offset:3072
	ds_read_b128 v[182:185], v229 offset:4096
	ds_read_b128 v[186:189], v229 offset:5120
	ds_read_b128 v[190:193], v229 offset:6144
	ds_read_b128 v[194:197], v229 offset:7168
	global_load_lds_dwordx4 v206, s[28:29]
	s_add_i32 m0, s40, 0xe000
	s_nop 0
	global_load_lds_dwordx4 v208, s[28:29]
	s_waitcnt vmcnt(8)
	s_waitcnt lgkmcnt(0)
	s_barrier
	s_setprio 1
	s_waitcnt lgkmcnt(0)
	v_mfma_f32_16x16x32_bf16 v[130:133], v[134:137], v[166:169], v[130:133]
	v_mfma_f32_16x16x32_bf16 v[122:125], v[142:145], v[166:169], v[122:125]
	v_mfma_f32_16x16x32_bf16 v[114:117], v[134:137], v[174:177], v[114:117]
	v_mfma_f32_16x16x32_bf16 v[106:109], v[142:145], v[174:177], v[106:109]
	v_mfma_f32_16x16x32_bf16 v[98:101], v[134:137], v[182:185], v[98:101]
	v_mfma_f32_16x16x32_bf16 v[90:93], v[142:145], v[182:185], v[90:93]
	v_mfma_f32_16x16x32_bf16 v[82:85], v[134:137], v[190:193], v[82:85]
	v_mfma_f32_16x16x32_bf16 v[74:77], v[142:145], v[190:193], v[74:77]
	v_mfma_f32_16x16x32_bf16 v[130:133], v[138:141], v[170:173], v[130:133]
	v_mfma_f32_16x16x32_bf16 v[122:125], v[146:149], v[170:173], v[122:125]
	v_mfma_f32_16x16x32_bf16 v[114:117], v[138:141], v[178:181], v[114:117]
	v_mfma_f32_16x16x32_bf16 v[106:109], v[146:149], v[178:181], v[106:109]
	v_mfma_f32_16x16x32_bf16 v[98:101], v[138:141], v[186:189], v[98:101]
	v_mfma_f32_16x16x32_bf16 v[90:93], v[146:149], v[186:189], v[90:93]
	v_mfma_f32_16x16x32_bf16 v[82:85], v[138:141], v[194:197], v[82:85]
	v_mfma_f32_16x16x32_bf16 v[74:77], v[146:149], v[194:197], v[74:77]
	s_setprio 0
	s_setprio 1
	v_mfma_f32_16x16x32_bf16 v[126:129], v[150:153], v[166:169], v[126:129]
	v_mfma_f32_16x16x32_bf16 v[118:121], v[158:161], v[166:169], v[118:121]
	v_mfma_f32_16x16x32_bf16 v[110:113], v[150:153], v[174:177], v[110:113]
	v_mfma_f32_16x16x32_bf16 v[102:105], v[158:161], v[174:177], v[102:105]
	v_mfma_f32_16x16x32_bf16 v[94:97], v[150:153], v[182:185], v[94:97]
	v_mfma_f32_16x16x32_bf16 v[86:89], v[158:161], v[182:185], v[86:89]
	v_mfma_f32_16x16x32_bf16 v[78:81], v[150:153], v[190:193], v[78:81]
	v_mfma_f32_16x16x32_bf16 v[70:73], v[158:161], v[190:193], v[70:73]
	v_mfma_f32_16x16x32_bf16 v[126:129], v[154:157], v[170:173], v[126:129]
	v_mfma_f32_16x16x32_bf16 v[118:121], v[162:165], v[170:173], v[118:121]
	v_mfma_f32_16x16x32_bf16 v[110:113], v[154:157], v[178:181], v[110:113]
	v_mfma_f32_16x16x32_bf16 v[102:105], v[162:165], v[178:181], v[102:105]
	v_mfma_f32_16x16x32_bf16 v[94:97], v[154:157], v[186:189], v[94:97]
	v_mfma_f32_16x16x32_bf16 v[86:89], v[162:165], v[186:189], v[86:89]
	v_mfma_f32_16x16x32_bf16 v[78:81], v[154:157], v[194:197], v[78:81]
	v_mfma_f32_16x16x32_bf16 v[70:73], v[162:165], v[194:197], v[70:73]
	s_setprio 0
	s_barrier
	s_add_i32 s62, s53, s12
	s_add_u32 s98, s46, s10
	s_addc_u32 s99, s47, s11
	s_mov_b32 m0, s62
	ds_read_b128 v[166:169], v229 offset:16384
	ds_read_b128 v[170:173], v229 offset:17408
	ds_read_b128 v[174:177], v229 offset:18432
	ds_read_b128 v[178:181], v229 offset:19456
	ds_read_b128 v[182:185], v229 offset:20480
	ds_read_b128 v[186:189], v229 offset:21504
	ds_read_b128 v[190:193], v229 offset:22528
	ds_read_b128 v[194:197], v229 offset:23552
	global_load_lds_dwordx4 v202, s[46:47]
	s_add_i32 m0, s62, 0x2000
	s_add_u32 s62, s46, 0x40000
	s_addc_u32 s63, s47, 0
	s_add_i32 s64, s54, s12
	global_load_lds_dwordx4 v198, s[46:47]
	s_mov_b32 m0, s64
	s_add_u32 s100, s48, s10
	s_addc_u32 s101, s49, s11
	global_load_lds_dwordx4 v202, s[62:63]
	s_add_i32 m0, s64, 0x2000
	s_nop 0
	global_load_lds_dwordx4 v198, s[62:63]
	s_mov_b32 m0, s40
	s_nop 0
	global_load_lds_dwordx4 v204, s[48:49]
	s_mov_b32 m0, s41
	s_nop 0
	global_load_lds_dwordx4 v200, s[48:49]
	s_waitcnt vmcnt(8)
	s_waitcnt lgkmcnt(0)
	s_barrier
	s_setprio 1
	s_waitcnt lgkmcnt(0)
	v_mfma_f32_16x16x32_bf16 v[66:69], v[134:137], v[166:169], v[66:69]
	v_mfma_f32_16x16x32_bf16 v[58:61], v[142:145], v[166:169], v[58:61]
	v_mfma_f32_16x16x32_bf16 v[50:53], v[134:137], v[174:177], v[50:53]
	v_mfma_f32_16x16x32_bf16 v[42:45], v[142:145], v[174:177], v[42:45]
	v_mfma_f32_16x16x32_bf16 v[34:37], v[134:137], v[182:185], v[34:37]
	v_mfma_f32_16x16x32_bf16 v[26:29], v[142:145], v[182:185], v[26:29]
	v_mfma_f32_16x16x32_bf16 v[18:21], v[134:137], v[190:193], v[18:21]
	v_mfma_f32_16x16x32_bf16 v[10:13], v[142:145], v[190:193], v[10:13]
	v_mfma_f32_16x16x32_bf16 v[66:69], v[138:141], v[170:173], v[66:69]
	v_mfma_f32_16x16x32_bf16 v[58:61], v[146:149], v[170:173], v[58:61]
	v_mfma_f32_16x16x32_bf16 v[50:53], v[138:141], v[178:181], v[50:53]
	v_mfma_f32_16x16x32_bf16 v[42:45], v[146:149], v[178:181], v[42:45]
	v_mfma_f32_16x16x32_bf16 v[34:37], v[138:141], v[186:189], v[34:37]
	v_mfma_f32_16x16x32_bf16 v[26:29], v[146:149], v[186:189], v[26:29]
	v_mfma_f32_16x16x32_bf16 v[18:21], v[138:141], v[194:197], v[18:21]
	v_mfma_f32_16x16x32_bf16 v[10:13], v[146:149], v[194:197], v[10:13]
	s_setprio 0
	s_setprio 1
	v_mfma_f32_16x16x32_bf16 v[62:65], v[150:153], v[166:169], v[62:65]
	v_mfma_f32_16x16x32_bf16 v[54:57], v[158:161], v[166:169], v[54:57]
	v_mfma_f32_16x16x32_bf16 v[46:49], v[150:153], v[174:177], v[46:49]
	v_mfma_f32_16x16x32_bf16 v[38:41], v[158:161], v[174:177], v[38:41]
	v_mfma_f32_16x16x32_bf16 v[30:33], v[150:153], v[182:185], v[30:33]
	v_mfma_f32_16x16x32_bf16 v[22:25], v[158:161], v[182:185], v[22:25]
	v_mfma_f32_16x16x32_bf16 v[14:17], v[150:153], v[190:193], v[14:17]
	v_mfma_f32_16x16x32_bf16 v[6:9], v[158:161], v[190:193], v[6:9]
	v_mfma_f32_16x16x32_bf16 v[62:65], v[154:157], v[170:173], v[62:65]
	v_mfma_f32_16x16x32_bf16 v[54:57], v[162:165], v[170:173], v[54:57]
	v_mfma_f32_16x16x32_bf16 v[46:49], v[154:157], v[178:181], v[46:49]
	v_mfma_f32_16x16x32_bf16 v[38:41], v[162:165], v[178:181], v[38:41]
	v_mfma_f32_16x16x32_bf16 v[30:33], v[154:157], v[186:189], v[30:33]
	v_mfma_f32_16x16x32_bf16 v[22:25], v[162:165], v[186:189], v[22:25]
	v_mfma_f32_16x16x32_bf16 v[14:17], v[154:157], v[194:197], v[14:17]
	v_mfma_f32_16x16x32_bf16 v[6:9], v[162:165], v[194:197], v[6:9]
	s_setprio 0
	s_barrier
	s_add_i32 s62, 0, 0x18000
	s_add_i32 s63, 0, 0x1c000
	v_add_u32_e32 v134, s62, v225
	v_add_u32_e32 v146, s63, v225
	ds_read_b128 v[150:153], v134
	ds_read_b128 v[154:157], v134 offset:1024
	ds_read_b128 v[158:161], v134 offset:2048
	ds_read_b128 v[162:165], v134 offset:3072
	ds_read_b128 v[134:137], v146
	ds_read_b128 v[138:141], v146 offset:1024
	ds_read_b128 v[142:145], v146 offset:2048
	ds_read_b128 v[146:149], v146 offset:3072
	s_add_u32 s48, s48, 0x40000
	s_addc_u32 s49, s49, 0
	s_mov_b32 m0, s42
	ds_read_b128 v[166:169], v229 offset:32768
	ds_read_b128 v[170:173], v229 offset:33792
	ds_read_b128 v[174:177], v229 offset:34816
	ds_read_b128 v[178:181], v229 offset:35840
	ds_read_b128 v[182:185], v229 offset:36864
	ds_read_b128 v[186:189], v229 offset:37888
	ds_read_b128 v[190:193], v229 offset:38912
	ds_read_b128 v[194:197], v229 offset:39936
	global_load_lds_dwordx4 v204, s[48:49]
	s_mov_b32 m0, s43
	s_nop 0
	global_load_lds_dwordx4 v200, s[48:49]
	s_waitcnt vmcnt(8)
	s_waitcnt lgkmcnt(0)
	s_barrier
	s_setprio 1
	s_waitcnt lgkmcnt(0)
	v_mfma_f32_16x16x32_bf16 v[130:133], v[150:153], v[166:169], v[130:133]
	v_mfma_f32_16x16x32_bf16 v[122:125], v[158:161], v[166:169], v[122:125]
	v_mfma_f32_16x16x32_bf16 v[114:117], v[150:153], v[174:177], v[114:117]
	v_mfma_f32_16x16x32_bf16 v[106:109], v[158:161], v[174:177], v[106:109]
	v_mfma_f32_16x16x32_bf16 v[98:101], v[150:153], v[182:185], v[98:101]
	v_mfma_f32_16x16x32_bf16 v[90:93], v[158:161], v[182:185], v[90:93]
	v_mfma_f32_16x16x32_bf16 v[82:85], v[150:153], v[190:193], v[82:85]
	v_mfma_f32_16x16x32_bf16 v[74:77], v[158:161], v[190:193], v[74:77]
	v_mfma_f32_16x16x32_bf16 v[130:133], v[154:157], v[170:173], v[130:133]
	v_mfma_f32_16x16x32_bf16 v[122:125], v[162:165], v[170:173], v[122:125]
	v_mfma_f32_16x16x32_bf16 v[114:117], v[154:157], v[178:181], v[114:117]
	v_mfma_f32_16x16x32_bf16 v[106:109], v[162:165], v[178:181], v[106:109]
	v_mfma_f32_16x16x32_bf16 v[98:101], v[154:157], v[186:189], v[98:101]
	v_mfma_f32_16x16x32_bf16 v[90:93], v[162:165], v[186:189], v[90:93]
	v_mfma_f32_16x16x32_bf16 v[82:85], v[154:157], v[194:197], v[82:85]
	v_mfma_f32_16x16x32_bf16 v[74:77], v[162:165], v[194:197], v[74:77]
	s_setprio 0
	s_setprio 1
	v_mfma_f32_16x16x32_bf16 v[126:129], v[134:137], v[166:169], v[126:129]
	v_mfma_f32_16x16x32_bf16 v[118:121], v[142:145], v[166:169], v[118:121]
	v_mfma_f32_16x16x32_bf16 v[110:113], v[134:137], v[174:177], v[110:113]
	v_mfma_f32_16x16x32_bf16 v[102:105], v[142:145], v[174:177], v[102:105]
	v_mfma_f32_16x16x32_bf16 v[94:97], v[134:137], v[182:185], v[94:97]
	v_mfma_f32_16x16x32_bf16 v[86:89], v[142:145], v[182:185], v[86:89]
	v_mfma_f32_16x16x32_bf16 v[78:81], v[134:137], v[190:193], v[78:81]
	v_mfma_f32_16x16x32_bf16 v[70:73], v[142:145], v[190:193], v[70:73]
	v_mfma_f32_16x16x32_bf16 v[126:129], v[138:141], v[170:173], v[126:129]
	v_mfma_f32_16x16x32_bf16 v[118:121], v[146:149], v[170:173], v[118:121]
	v_mfma_f32_16x16x32_bf16 v[110:113], v[138:141], v[178:181], v[110:113]
	v_mfma_f32_16x16x32_bf16 v[102:105], v[146:149], v[178:181], v[102:105]
	v_mfma_f32_16x16x32_bf16 v[94:97], v[138:141], v[186:189], v[94:97]
	v_mfma_f32_16x16x32_bf16 v[86:89], v[146:149], v[186:189], v[86:89]
	v_mfma_f32_16x16x32_bf16 v[78:81], v[138:141], v[194:197], v[78:81]
	v_mfma_f32_16x16x32_bf16 v[70:73], v[146:149], v[194:197], v[70:73]
	s_setprio 0
	s_barrier
	s_add_i32 s48, s62, s12
	s_mov_b32 m0, s48
	ds_read_b128 v[190:193], v229 offset:49152
	ds_read_b128 v[194:197], v229 offset:50176
	ds_read_b128 v[182:185], v229 offset:51200
	ds_read_b128 v[186:189], v229 offset:52224
	ds_read_b128 v[174:177], v229 offset:53248
	ds_read_b128 v[178:181], v229 offset:54272
	ds_read_b128 v[166:169], v229 offset:55296
	ds_read_b128 v[170:173], v229 offset:56320
	global_load_lds_dwordx4 v202, s[98:99]
	s_add_i32 m0, s48, 0x2000
	s_add_u32 s46, s46, 0x40080
	s_addc_u32 s47, s47, 0
	s_add_i32 s48, s63, s12
	global_load_lds_dwordx4 v198, s[98:99]
	s_mov_b32 m0, s48
	s_andn2_b64 vcc, exec, s[30:31]
	global_load_lds_dwordx4 v202, s[46:47]
	s_add_i32 m0, s48, 0x2000
	s_nop 0
	global_load_lds_dwordx4 v198, s[46:47]
	s_mov_b32 m0, s51
	s_nop 0
	global_load_lds_dwordx4 v204, s[100:101]
	s_mov_b32 m0, s52
	s_nop 0
	global_load_lds_dwordx4 v200, s[100:101]
	s_waitcnt vmcnt(8)
	s_cbranch_vccnz .LBB0_329
	s_and_saveexec_b64 s[30:31], s[4:5]
	s_cbranch_execz .LBB0_328
	v_mov_b32_e32 v232, v3
	v_mov_b32_e32 v233, v4
	v_mov_b32_e32 v234, v2
	v_mov_b32_e32 v235, v5
	v_pk_add_f32 v[232:233], v[232:233], v[234:235]
	s_nop 0
	v_add_f32_e32 v226, v232, v233
	v_fmamk_f32 v226, v226, 0x3a800000, v230
	ds_write_b32 v228, v226
	s_branch .LBB0_328

.LBB0_1406:
.Lcv_t2_tr:
	s_waitcnt lgkmcnt(0)
	v_add_u32_e32 v16, s24, v8
	ds_read2_b32 v[2:3], v26 offset1:36
	s_ashr_i32 s17, s16, 31
	v_ashrrev_i32_e32 v17, 31, v16
	s_waitcnt lgkmcnt(0)
	v_cvt_pk_bf16_f32 v2, v2, v3
	ds_read2_b32 v[4:5], v26 offset0:72 offset1:108
	v_lshl_add_u64 v[28:29], s[16:17], 1, v[14:15]
	v_lshlrev_b64 v[30:31], 11, v[16:17]
	s_waitcnt lgkmcnt(0)
	v_cvt_pk_bf16_f32 v3, v4, v5
	ds_read2_b32 v[4:5], v26 offset0:144 offset1:180
	v_lshl_add_u64 v[30:31], v[28:29], 0, v[30:31]
	s_waitcnt lgkmcnt(0)
	v_cvt_pk_bf16_f32 v4, v4, v5
	ds_read2_b32 v[6:7], v26 offset0:216 offset1:252
	s_waitcnt lgkmcnt(0)
	v_cvt_pk_bf16_f32 v5, v6, v7
	global_store_dwordx4 v[30:31], v[2:5], off
	v_add_u32_e32 v30, 8, v16
	v_ashrrev_i32_e32 v31, 31, v30
	ds_read2_b32 v[6:7], v26 offset0:8 offset1:44
	s_waitcnt lgkmcnt(0)
	v_cvt_pk_bf16_f32 v2, v6, v7
	ds_read2_b32 v[4:5], v26 offset0:80 offset1:116
	v_lshlrev_b64 v[30:31], 11, v[30:31]
	s_waitcnt lgkmcnt(0)
	v_cvt_pk_bf16_f32 v3, v4, v5
	ds_read2_b32 v[4:5], v26 offset0:152 offset1:188
	v_add_u32_e32 v11, 0x200, v26
	v_lshl_add_u64 v[30:31], v[28:29], 0, v[30:31]
	s_waitcnt lgkmcnt(0)
	v_cvt_pk_bf16_f32 v4, v4, v5
	ds_read2_b32 v[6:7], v11 offset0:96 offset1:132
	s_waitcnt lgkmcnt(0)
	v_cvt_pk_bf16_f32 v5, v6, v7
	global_store_dwordx4 v[30:31], v[2:5], off
	v_add_u32_e32 v30, 16, v16
	ds_read2_b32 v[6:7], v26 offset0:16 offset1:52
	s_waitcnt lgkmcnt(0)
	v_cvt_pk_bf16_f32 v2, v6, v7
	ds_read2_b32 v[4:5], v26 offset0:88 offset1:124
	v_ashrrev_i32_e32 v31, 31, v30
	s_waitcnt lgkmcnt(0)
	v_cvt_pk_bf16_f32 v3, v4, v5
	ds_read2_b32 v[4:5], v26 offset0:160 offset1:196
	v_lshlrev_b64 v[30:31], 11, v[30:31]
	v_add_u32_e32 v16, 24, v16
	s_waitcnt lgkmcnt(0)
	v_cvt_pk_bf16_f32 v4, v4, v5
	ds_read2_b32 v[6:7], v11 offset0:104 offset1:140
	s_waitcnt lgkmcnt(0)
	v_cvt_pk_bf16_f32 v5, v6, v7
	v_lshl_add_u64 v[30:31], v[28:29], 0, v[30:31]
	v_ashrrev_i32_e32 v17, 31, v16
	ds_read2_b32 v[6:7], v26 offset0:24 offset1:60
	global_store_dwordx4 v[30:31], v[2:5], off
	v_lshlrev_b64 v[16:17], 11, v[16:17]
	v_lshl_add_u64 v[16:17], v[28:29], 0, v[16:17]
	s_waitcnt lgkmcnt(0)
	v_cvt_pk_bf16_f32 v2, v6, v7
	ds_read2_b32 v[4:5], v26 offset0:96 offset1:132
	s_waitcnt lgkmcnt(0)
	v_cvt_pk_bf16_f32 v3, v4, v5
	ds_read2_b32 v[4:5], v26 offset0:168 offset1:204
	s_waitcnt lgkmcnt(0)
	v_cvt_pk_bf16_f32 v4, v4, v5
	ds_read2_b32 v[6:7], v11 offset0:112 offset1:148
	s_waitcnt lgkmcnt(0)
	v_cvt_pk_bf16_f32 v5, v6, v7
	global_store_dwordx4 v[16:17], v[2:5], off
	s_waitcnt lgkmcnt(0)
	s_add_i32 s16, s23, 0x400
	s_add_i32 s22, s22, 0x8000
	s_addk_i32 s14, 0x4000
	s_cmpk_lt_i32 s23, 0x700
	s_mov_b32 s23, s16
	s_cbranch_scc0 .LBB0_1431
.LBB0_1407:
	s_mul_hi_i32 s16, s23, 0x2e8ba2e9
	s_lshr_b32 s17, s16, 31
	s_ashr_i32 s16, s16, 5
	s_add_i32 s17, s16, s17
	s_mul_i32 s18, s17, 0xffffea00
	s_lshl_b32 s16, s17, 6
	s_add_i32 s24, s22, s18
	s_bitcmp0_b32 s23, 2
	s_mulk_i32 s17, 0xf500
	s_cselect_b32 s19, s11, s7
	s_cselect_b32 s18, s10, s6
	s_add_i32 s17, s14, s17
	s_and_b32 s20, s17, 0xffffff80
	s_ashr_i32 s21, s20, 31
	s_lshl_b64 s[20:21], s[20:21], 2
	s_add_u32 s20, s18, s20
	s_addc_u32 s21, s19, s21
	s_and_b32 s17, s24, 0x60
	v_or_b32_e32 v2, s17, v18
	s_cmp_lg_u64 s[18:19], 0
	v_or_b32_e32 v6, s16, v8
	v_lshlrev_b32_e32 v12, 2, v2
	s_cselect_b64 s[18:19], -1, 0
	v_lshl_add_u64 v[16:17], s[20:21], 0, v[12:13]
	v_mov_b32_e32 v80, v6
	v_cmp_gt_i32_e32 vcc, s2, v80
	s_and_b64 s[98:99], s[18:19], vcc
	v_mov_b32_e32 v96, 0
	v_mov_b32_e32 v97, 0
	v_mov_b32_e32 v98, 0
	v_mov_b32_e32 v99, 0
	v_mov_b32_e32 v160, 1.0
	s_and_saveexec_b64 s[100:101], s[98:99]
	v_mad_i64_i32 v[128:129], s[98:99], v80, s15, v[16:17]
	global_load_dwordx4 v[96:99], v[128:129], off nt
	s_and_b64 vcc, exec, s[4:5]
	s_cbranch_vccnz .Lcv_t2_ng0
	v_ashrrev_i32_e32 v81, 31, v80
	v_lshl_add_u64 v[144:145], v[80:81], 2, s[8:9]
	global_load_dword v160, v[144:145], off
.Lcv_t2_ng0:
	s_or_b64 exec, exec, s[100:101]
	v_or_b32_e32 v82, s16, v19
	v_cmp_gt_i32_e32 vcc, s2, v82
	s_and_b64 s[98:99], s[18:19], vcc
	v_mov_b32_e32 v100, 0
	v_mov_b32_e32 v101, 0
	v_mov_b32_e32 v102, 0
	v_mov_b32_e32 v103, 0
	v_mov_b32_e32 v161, 1.0
	s_and_saveexec_b64 s[100:101], s[98:99]
	v_mad_i64_i32 v[130:131], s[98:99], v82, s15, v[16:17]
	global_load_dwordx4 v[100:103], v[130:131], off nt
	s_and_b64 vcc, exec, s[4:5]
	s_cbranch_vccnz .Lcv_t2_ng1
	v_ashrrev_i32_e32 v83, 31, v82
	v_lshl_add_u64 v[146:147], v[82:83], 2, s[8:9]
	global_load_dword v161, v[146:147], off
.Lcv_t2_ng1:
	s_or_b64 exec, exec, s[100:101]
	v_or_b32_e32 v84, s16, v20
	v_cmp_gt_i32_e32 vcc, s2, v84
	s_and_b64 s[98:99], s[18:19], vcc
	v_mov_b32_e32 v104, 0
	v_mov_b32_e32 v105, 0
	v_mov_b32_e32 v106, 0
	v_mov_b32_e32 v107, 0
	v_mov_b32_e32 v162, 1.0
	s_and_saveexec_b64 s[100:101], s[98:99]
	v_mad_i64_i32 v[132:133], s[98:99], v84, s15, v[16:17]
	global_load_dwordx4 v[104:107], v[132:133], off nt
	s_and_b64 vcc, exec, s[4:5]
	s_cbranch_vccnz .Lcv_t2_ng2
	v_ashrrev_i32_e32 v85, 31, v84
	v_lshl_add_u64 v[148:149], v[84:85], 2, s[8:9]
	global_load_dword v162, v[148:149], off
.Lcv_t2_ng2:
	s_or_b64 exec, exec, s[100:101]
	v_or_b32_e32 v86, s16, v21
	v_cmp_gt_i32_e32 vcc, s2, v86
	s_and_b64 s[98:99], s[18:19], vcc
	v_mov_b32_e32 v108, 0
	v_mov_b32_e32 v109, 0
	v_mov_b32_e32 v110, 0
	v_mov_b32_e32 v111, 0
	v_mov_b32_e32 v163, 1.0
	s_and_saveexec_b64 s[100:101], s[98:99]
	v_mad_i64_i32 v[134:135], s[98:99], v86, s15, v[16:17]
	global_load_dwordx4 v[108:111], v[134:135], off nt
	s_and_b64 vcc, exec, s[4:5]
	s_cbranch_vccnz .Lcv_t2_ng3
	v_ashrrev_i32_e32 v87, 31, v86
	v_lshl_add_u64 v[150:151], v[86:87], 2, s[8:9]
	global_load_dword v163, v[150:151], off
.Lcv_t2_ng3:
	s_or_b64 exec, exec, s[100:101]
	v_or_b32_e32 v88, s16, v22
	v_cmp_gt_i32_e32 vcc, s2, v88
	s_and_b64 s[98:99], s[18:19], vcc
	v_mov_b32_e32 v112, 0
	v_mov_b32_e32 v113, 0
	v_mov_b32_e32 v114, 0
	v_mov_b32_e32 v115, 0
	v_mov_b32_e32 v164, 1.0
	s_and_saveexec_b64 s[100:101], s[98:99]
	v_mad_i64_i32 v[136:137], s[98:99], v88, s15, v[16:17]
	global_load_dwordx4 v[112:115], v[136:137], off nt
	s_and_b64 vcc, exec, s[4:5]
	s_cbranch_vccnz .Lcv_t2_ng4
	v_ashrrev_i32_e32 v89, 31, v88
	v_lshl_add_u64 v[152:153], v[88:89], 2, s[8:9]
	global_load_dword v164, v[152:153], off
.Lcv_t2_ng4:
	s_or_b64 exec, exec, s[100:101]
	v_or_b32_e32 v90, s16, v23
	v_cmp_gt_i32_e32 vcc, s2, v90
	s_and_b64 s[98:99], s[18:19], vcc
	v_mov_b32_e32 v116, 0
	v_mov_b32_e32 v117, 0
	v_mov_b32_e32 v118, 0
	v_mov_b32_e32 v119, 0
	v_mov_b32_e32 v165, 1.0
	s_and_saveexec_b64 s[100:101], s[98:99]
	v_mad_i64_i32 v[138:139], s[98:99], v90, s15, v[16:17]
	global_load_dwordx4 v[116:119], v[138:139], off nt
	s_and_b64 vcc, exec, s[4:5]
	s_cbranch_vccnz .Lcv_t2_ng5
	v_ashrrev_i32_e32 v91, 31, v90
	v_lshl_add_u64 v[154:155], v[90:91], 2, s[8:9]
	global_load_dword v165, v[154:155], off
.Lcv_t2_ng5:
	s_or_b64 exec, exec, s[100:101]
	v_or_b32_e32 v92, s16, v24
	v_cmp_gt_i32_e32 vcc, s2, v92
	s_and_b64 s[98:99], s[18:19], vcc
	v_mov_b32_e32 v120, 0
	v_mov_b32_e32 v121, 0
	v_mov_b32_e32 v122, 0
	v_mov_b32_e32 v123, 0
	v_mov_b32_e32 v166, 1.0
	s_and_saveexec_b64 s[100:101], s[98:99]
	v_mad_i64_i32 v[140:141], s[98:99], v92, s15, v[16:17]
	global_load_dwordx4 v[120:123], v[140:141], off nt
	s_and_b64 vcc, exec, s[4:5]
	s_cbranch_vccnz .Lcv_t2_ng6
	v_ashrrev_i32_e32 v93, 31, v92
	v_lshl_add_u64 v[156:157], v[92:93], 2, s[8:9]
	global_load_dword v166, v[156:157], off
.Lcv_t2_ng6:
	s_or_b64 exec, exec, s[100:101]
	v_or_b32_e32 v94, s16, v25
	v_cmp_gt_i32_e32 vcc, s2, v94
	s_and_b64 s[98:99], s[18:19], vcc
	v_mov_b32_e32 v124, 0
	v_mov_b32_e32 v125, 0
	v_mov_b32_e32 v126, 0
	v_mov_b32_e32 v127, 0
	v_mov_b32_e32 v167, 1.0
	s_and_saveexec_b64 s[100:101], s[98:99]
	v_mad_i64_i32 v[142:143], s[98:99], v94, s15, v[16:17]
	global_load_dwordx4 v[124:127], v[142:143], off nt
	s_and_b64 vcc, exec, s[4:5]
	s_cbranch_vccnz .Lcv_t2_ng7
	v_ashrrev_i32_e32 v95, 31, v94
	v_lshl_add_u64 v[158:159], v[94:95], 2, s[8:9]
	global_load_dword v167, v[158:159], off
.Lcv_t2_ng7:
	s_or_b64 exec, exec, s[100:101]
	s_waitcnt vmcnt(0)
	v_mul_f32_e32 v96, v96, v160
	v_mul_f32_e32 v97, v97, v160
	v_mul_f32_e32 v98, v98, v160
	v_mul_f32_e32 v99, v99, v160
	v_mul_f32_e32 v100, v100, v161
	v_mul_f32_e32 v101, v101, v161
	v_mul_f32_e32 v102, v102, v161
	v_mul_f32_e32 v103, v103, v161
	v_mul_f32_e32 v104, v104, v162
	v_mul_f32_e32 v105, v105, v162
	v_mul_f32_e32 v106, v106, v162
	v_mul_f32_e32 v107, v107, v162
	v_mul_f32_e32 v108, v108, v163
	v_mul_f32_e32 v109, v109, v163
	v_mul_f32_e32 v110, v110, v163
	v_mul_f32_e32 v111, v111, v163
	v_mul_f32_e32 v112, v112, v164
	v_mul_f32_e32 v113, v113, v164
	v_mul_f32_e32 v114, v114, v164
	v_mul_f32_e32 v115, v115, v164
	v_mul_f32_e32 v116, v116, v165
	v_mul_f32_e32 v117, v117, v165
	v_mul_f32_e32 v118, v118, v165
	v_mul_f32_e32 v119, v119, v165
	v_mul_f32_e32 v120, v120, v166
	v_mul_f32_e32 v121, v121, v166
	v_mul_f32_e32 v122, v122, v166
	v_mul_f32_e32 v123, v123, v166
	v_mul_f32_e32 v124, v124, v167
	v_mul_f32_e32 v125, v125, v167
	v_mul_f32_e32 v126, v126, v167
	v_mul_f32_e32 v127, v127, v167
	ds_write_b128 v27, v[96:99]
	ds_write_b128 v27, v[100:103] offset:1152
	ds_write_b128 v27, v[104:107] offset:2304
	ds_write_b128 v27, v[108:111] offset:3456
	ds_write_b128 v27, v[112:115] offset:4608
	ds_write_b128 v27, v[116:119] offset:5760
	ds_write_b128 v27, v[120:123] offset:6912
	ds_write_b128 v27, v[124:127] offset:8064
	s_branch .Lcv_t2_tr

.LBB0_1432:
.Lcv_t3_tr:
	s_waitcnt lgkmcnt(0)
	v_or_b32_e32 v11, s15, v8
	ds_read2_b32 v[2:3], v26 offset1:36
	s_ashr_i32 s9, s8, 31
	v_mul_i32_i24_e32 v16, 0x1600, v11
	s_waitcnt lgkmcnt(0)
	v_cvt_pk_bf16_f32 v2, v2, v3
	ds_read2_b32 v[4:5], v26 offset0:72 offset1:108
	v_lshl_add_u64 v[14:15], s[8:9], 1, v[12:13]
	v_ashrrev_i32_e32 v17, 31, v16
	s_waitcnt lgkmcnt(0)
	v_cvt_pk_bf16_f32 v3, v4, v5
	ds_read2_b32 v[4:5], v26 offset0:144 offset1:180
	v_lshl_add_u64 v[16:17], v[14:15], 0, v[16:17]
	s_waitcnt lgkmcnt(0)
	v_cvt_pk_bf16_f32 v4, v4, v5
	ds_read2_b32 v[6:7], v26 offset0:216 offset1:252
	s_waitcnt lgkmcnt(0)
	v_cvt_pk_bf16_f32 v5, v6, v7
	global_store_dwordx4 v[16:17], v[2:5], off
	v_or_b32_e32 v16, s15, v19
	v_mul_i32_i24_e32 v16, 0x1600, v16
	ds_read2_b32 v[6:7], v26 offset0:8 offset1:44
	s_waitcnt lgkmcnt(0)
	v_cvt_pk_bf16_f32 v2, v6, v7
	ds_read2_b32 v[4:5], v26 offset0:80 offset1:116
	v_ashrrev_i32_e32 v17, 31, v16
	s_waitcnt lgkmcnt(0)
	v_cvt_pk_bf16_f32 v3, v4, v5
	ds_read2_b32 v[4:5], v26 offset0:152 offset1:188
	v_add_u32_e32 v11, 0x200, v26
	v_lshl_add_u64 v[16:17], v[14:15], 0, v[16:17]
	s_waitcnt lgkmcnt(0)
	v_cvt_pk_bf16_f32 v4, v4, v5
	ds_read2_b32 v[6:7], v11 offset0:96 offset1:132
	s_waitcnt lgkmcnt(0)
	v_cvt_pk_bf16_f32 v5, v6, v7
	global_store_dwordx4 v[16:17], v[2:5], off
	v_or_b32_e32 v16, s15, v20
	ds_read2_b32 v[6:7], v26 offset0:16 offset1:52
	s_waitcnt lgkmcnt(0)
	v_cvt_pk_bf16_f32 v2, v6, v7
	ds_read2_b32 v[4:5], v26 offset0:88 offset1:124
	v_mul_i32_i24_e32 v16, 0x1600, v16
	s_waitcnt lgkmcnt(0)
	v_cvt_pk_bf16_f32 v3, v4, v5
	ds_read2_b32 v[4:5], v26 offset0:160 offset1:196
	v_ashrrev_i32_e32 v17, 31, v16
	s_waitcnt lgkmcnt(0)
	v_cvt_pk_bf16_f32 v4, v4, v5
	ds_read2_b32 v[6:7], v11 offset0:104 offset1:140
	s_waitcnt lgkmcnt(0)
	v_cvt_pk_bf16_f32 v5, v6, v7
	v_lshl_add_u64 v[16:17], v[14:15], 0, v[16:17]
	ds_read2_b32 v[6:7], v26 offset0:24 offset1:60
	global_store_dwordx4 v[16:17], v[2:5], off
	s_add_i32 s8, s14, 0x400
	s_cmpk_lt_u32 s14, 0xc80
	s_waitcnt lgkmcnt(0)
	v_cvt_pk_bf16_f32 v2, v6, v7
	ds_read2_b32 v[4:5], v26 offset0:96 offset1:132
	s_waitcnt lgkmcnt(0)
	v_cvt_pk_bf16_f32 v3, v4, v5
	ds_read2_b32 v[4:5], v26 offset0:168 offset1:204
	s_waitcnt lgkmcnt(0)
	v_cvt_pk_bf16_f32 v4, v4, v5
	v_or_b32_e32 v5, s15, v21
	v_mul_i32_i24_e32 v16, 0x1600, v5
	ds_read2_b32 v[6:7], v11 offset0:112 offset1:148
	v_ashrrev_i32_e32 v17, 31, v16
	s_waitcnt lgkmcnt(0)
	v_cvt_pk_bf16_f32 v5, v6, v7
	v_lshl_add_u64 v[6:7], v[14:15], 0, v[16:17]
	global_store_dwordx4 v[6:7], v[2:5], off
	s_waitcnt lgkmcnt(0)
	s_mov_b32 s14, s8
	s_cbranch_scc0 .LBB0_1449
.LBB0_1433:
	s_add_i32 s8, s14, 0xf500
	s_sext_i32_i16 s9, s8
	s_bfe_u32 s9, s9, 0x5001a
	s_add_i32 s9, s8, s9
	s_sext_i32_i16 s10, s9
	s_and_b32 s9, s9, 0xffe0
	s_sub_i32 s8, s8, s9
	s_sext_i32_i16 s9, s8
	s_lshl_b32 s8, s10, 1
	s_andn2_b32 s8, s8, 63
	s_lshl_b32 s15, s9, 5
	v_or_b32_e32 v2, s15, v18
	v_or_b32_e32 v6, s8, v8
	v_ashrrev_i32_e32 v3, 31, v2
	v_lshl_add_u64 v[14:15], v[2:3], 2, s[4:5]
	v_mov_b32_e32 v80, v6
	v_cmp_gt_i32_e32 vcc, s2, v80
	s_and_b64 s[98:99], s[6:7], vcc
	v_mov_b32_e32 v96, 0
	v_mov_b32_e32 v97, 0
	v_mov_b32_e32 v98, 0
	v_mov_b32_e32 v99, 0
	s_and_saveexec_b64 s[100:101], s[98:99]
	v_ashrrev_i32_e32 v81, 31, v80
	v_lshlrev_b64 v[128:129], 12, v[80:81]
	v_lshl_add_u64 v[128:129], v[14:15], 0, v[128:129]
	global_load_dwordx4 v[96:99], v[128:129], off nt
	s_or_b64 exec, exec, s[100:101]
	v_or_b32_e32 v82, s8, v19
	v_cmp_gt_i32_e32 vcc, s2, v82
	s_and_b64 s[98:99], s[6:7], vcc
	v_mov_b32_e32 v100, 0
	v_mov_b32_e32 v101, 0
	v_mov_b32_e32 v102, 0
	v_mov_b32_e32 v103, 0
	s_and_saveexec_b64 s[100:101], s[98:99]
	v_ashrrev_i32_e32 v83, 31, v82
	v_lshlrev_b64 v[130:131], 12, v[82:83]
	v_lshl_add_u64 v[130:131], v[14:15], 0, v[130:131]
	global_load_dwordx4 v[100:103], v[130:131], off nt
	s_or_b64 exec, exec, s[100:101]
	v_or_b32_e32 v84, s8, v20
	v_cmp_gt_i32_e32 vcc, s2, v84
	s_and_b64 s[98:99], s[6:7], vcc
	v_mov_b32_e32 v104, 0
	v_mov_b32_e32 v105, 0
	v_mov_b32_e32 v106, 0
	v_mov_b32_e32 v107, 0
	s_and_saveexec_b64 s[100:101], s[98:99]
	v_ashrrev_i32_e32 v85, 31, v84
	v_lshlrev_b64 v[132:133], 12, v[84:85]
	v_lshl_add_u64 v[132:133], v[14:15], 0, v[132:133]
	global_load_dwordx4 v[104:107], v[132:133], off nt
	s_or_b64 exec, exec, s[100:101]
	v_or_b32_e32 v86, s8, v21
	v_cmp_gt_i32_e32 vcc, s2, v86
	s_and_b64 s[98:99], s[6:7], vcc
	v_mov_b32_e32 v108, 0
	v_mov_b32_e32 v109, 0
	v_mov_b32_e32 v110, 0
	v_mov_b32_e32 v111, 0
	s_and_saveexec_b64 s[100:101], s[98:99]
	v_ashrrev_i32_e32 v87, 31, v86
	v_lshlrev_b64 v[134:135], 12, v[86:87]
	v_lshl_add_u64 v[134:135], v[14:15], 0, v[134:135]
	global_load_dwordx4 v[108:111], v[134:135], off nt
	s_or_b64 exec, exec, s[100:101]
	v_or_b32_e32 v88, s8, v22
	v_cmp_gt_i32_e32 vcc, s2, v88
	s_and_b64 s[98:99], s[6:7], vcc
	v_mov_b32_e32 v112, 0
	v_mov_b32_e32 v113, 0
	v_mov_b32_e32 v114, 0
	v_mov_b32_e32 v115, 0
	s_and_saveexec_b64 s[100:101], s[98:99]
	v_ashrrev_i32_e32 v89, 31, v88
	v_lshlrev_b64 v[136:137], 12, v[88:89]
	v_lshl_add_u64 v[136:137], v[14:15], 0, v[136:137]
	global_load_dwordx4 v[112:115], v[136:137], off nt
	s_or_b64 exec, exec, s[100:101]
	v_or_b32_e32 v90, s8, v23
	v_cmp_gt_i32_e32 vcc, s2, v90
	s_and_b64 s[98:99], s[6:7], vcc
	v_mov_b32_e32 v116, 0
	v_mov_b32_e32 v117, 0
	v_mov_b32_e32 v118, 0
	v_mov_b32_e32 v119, 0
	s_and_saveexec_b64 s[100:101], s[98:99]
	v_ashrrev_i32_e32 v91, 31, v90
	v_lshlrev_b64 v[138:139], 12, v[90:91]
	v_lshl_add_u64 v[138:139], v[14:15], 0, v[138:139]
	global_load_dwordx4 v[116:119], v[138:139], off nt
	s_or_b64 exec, exec, s[100:101]
	v_or_b32_e32 v92, s8, v24
	v_cmp_gt_i32_e32 vcc, s2, v92
	s_and_b64 s[98:99], s[6:7], vcc
	v_mov_b32_e32 v120, 0
	v_mov_b32_e32 v121, 0
	v_mov_b32_e32 v122, 0
	v_mov_b32_e32 v123, 0
	s_and_saveexec_b64 s[100:101], s[98:99]
	v_ashrrev_i32_e32 v93, 31, v92
	v_lshlrev_b64 v[140:141], 12, v[92:93]
	v_lshl_add_u64 v[140:141], v[14:15], 0, v[140:141]
	global_load_dwordx4 v[120:123], v[140:141], off nt
	s_or_b64 exec, exec, s[100:101]
	v_or_b32_e32 v94, s8, v25
	v_cmp_gt_i32_e32 vcc, s2, v94
	s_and_b64 s[98:99], s[6:7], vcc
	v_mov_b32_e32 v124, 0
	v_mov_b32_e32 v125, 0
	v_mov_b32_e32 v126, 0
	v_mov_b32_e32 v127, 0
	s_and_saveexec_b64 s[100:101], s[98:99]
	v_ashrrev_i32_e32 v95, 31, v94
	v_lshlrev_b64 v[142:143], 12, v[94:95]
	v_lshl_add_u64 v[142:143], v[14:15], 0, v[142:143]
	global_load_dwordx4 v[124:127], v[142:143], off nt
	s_or_b64 exec, exec, s[100:101]
	s_waitcnt vmcnt(0)
	ds_write_b128 v27, v[96:99]
	ds_write_b128 v27, v[100:103] offset:1152
	ds_write_b128 v27, v[104:107] offset:2304
	ds_write_b128 v27, v[108:111] offset:3456
	ds_write_b128 v27, v[112:115] offset:4608
	ds_write_b128 v27, v[116:119] offset:5760
	ds_write_b128 v27, v[120:123] offset:6912
	ds_write_b128 v27, v[124:127] offset:8064
	s_branch .Lcv_t3_tr

.LBB0_1451:
.Lcv_t6_tr:
	s_sub_i32 s10, 0, s9
	s_waitcnt lgkmcnt(0)
	s_add_i32 s10, s10, s13
	v_add_u32_e32 v16, s10, v28
	ds_read2_b32 v[2:3], v26 offset1:36
	s_ashr_i32 s9, s8, 31
	v_ashrrev_i32_e32 v17, 31, v16
	s_waitcnt lgkmcnt(0)
	v_cvt_pk_bf16_f32 v2, v2, v3
	ds_read2_b32 v[4:5], v26 offset0:72 offset1:108
	v_lshl_add_u64 v[14:15], s[8:9], 1, v[12:13]
	v_lshlrev_b64 v[30:31], 11, v[16:17]
	s_waitcnt lgkmcnt(0)
	v_cvt_pk_bf16_f32 v3, v4, v5
	ds_read2_b32 v[4:5], v26 offset0:144 offset1:180
	v_lshl_add_u64 v[30:31], v[14:15], 0, v[30:31]
	s_waitcnt lgkmcnt(0)
	v_cvt_pk_bf16_f32 v4, v4, v5
	ds_read2_b32 v[6:7], v26 offset0:216 offset1:252
	s_waitcnt lgkmcnt(0)
	v_cvt_pk_bf16_f32 v5, v6, v7
	global_store_dwordx4 v[30:31], v[2:5], off
	v_add_u32_e32 v30, 8, v16
	v_ashrrev_i32_e32 v31, 31, v30
	ds_read2_b32 v[6:7], v26 offset0:8 offset1:44
	s_waitcnt lgkmcnt(0)
	v_cvt_pk_bf16_f32 v2, v6, v7
	ds_read2_b32 v[4:5], v26 offset0:80 offset1:116
	v_lshlrev_b64 v[30:31], 11, v[30:31]
	s_waitcnt lgkmcnt(0)
	v_cvt_pk_bf16_f32 v3, v4, v5
	ds_read2_b32 v[4:5], v26 offset0:152 offset1:188
	v_add_u32_e32 v17, 0x200, v26
	v_lshl_add_u64 v[30:31], v[14:15], 0, v[30:31]
	s_waitcnt lgkmcnt(0)
	v_cvt_pk_bf16_f32 v4, v4, v5
	ds_read2_b32 v[6:7], v17 offset0:96 offset1:132
	s_waitcnt lgkmcnt(0)
	v_cvt_pk_bf16_f32 v5, v6, v7
	global_store_dwordx4 v[30:31], v[2:5], off
	v_add_u32_e32 v30, 16, v16
	ds_read2_b32 v[6:7], v26 offset0:16 offset1:52
	s_waitcnt lgkmcnt(0)
	v_cvt_pk_bf16_f32 v2, v6, v7
	ds_read2_b32 v[4:5], v26 offset0:88 offset1:124
	v_ashrrev_i32_e32 v31, 31, v30
	s_waitcnt lgkmcnt(0)
	v_cvt_pk_bf16_f32 v3, v4, v5
	ds_read2_b32 v[4:5], v26 offset0:160 offset1:196
	v_lshlrev_b64 v[30:31], 11, v[30:31]
	s_waitcnt lgkmcnt(0)
	v_cvt_pk_bf16_f32 v4, v4, v5
	ds_read2_b32 v[6:7], v17 offset0:104 offset1:140
	s_waitcnt lgkmcnt(0)
	v_cvt_pk_bf16_f32 v5, v6, v7
	v_lshl_add_u64 v[30:31], v[14:15], 0, v[30:31]
	ds_read2_b32 v[6:7], v26 offset0:24 offset1:60
	global_store_dwordx4 v[30:31], v[2:5], off
	v_add_u32_e32 v16, 24, v16
	s_add_i32 s8, s12, 0x400
	s_waitcnt lgkmcnt(0)
	v_cvt_pk_bf16_f32 v2, v6, v7
	ds_read2_b32 v[4:5], v26 offset0:96 offset1:132
	s_waitcnt lgkmcnt(0)
	v_cvt_pk_bf16_f32 v3, v4, v5
	ds_read2_b32 v[4:5], v26 offset0:168 offset1:204
	s_waitcnt lgkmcnt(0)
	v_cvt_pk_bf16_f32 v4, v4, v5
	ds_read2_b32 v[6:7], v17 offset0:112 offset1:148
	v_ashrrev_i32_e32 v17, 31, v16
	v_lshlrev_b64 v[16:17], 11, v[16:17]
	v_lshl_add_u64 v[14:15], v[14:15], 0, v[16:17]
	s_waitcnt lgkmcnt(0)
	v_cvt_pk_bf16_f32 v5, v6, v7
	global_store_dwordx4 v[14:15], v[2:5], off
	s_waitcnt lgkmcnt(0)
	v_add_u32_e32 v28, 0x8000, v28
	v_add_u32_e32 v11, 0x8000, v11
	s_cmpk_lt_i32 s12, 0xfe00
	s_mov_b32 s12, s8
	s_cbranch_scc0 .LBB0_1468
.LBB0_1452:
	s_ashr_i32 s8, s12, 31
	s_lshr_b32 s8, s8, 27
	s_add_i32 s8, s12, s8
	s_ashr_i32 s9, s8, 5
	s_lshl_b32 s8, s9, 6
	s_lshl_b32 s9, s9, 10
	s_sub_i32 s10, s13, s9
	v_add_u32_e32 v2, s10, v11
	v_or_b32_e32 v6, s8, v8
	v_ashrrev_i32_e32 v3, 31, v2
	v_lshl_add_u64 v[14:15], v[2:3], 2, s[4:5]
	v_mov_b32_e32 v80, v6
	v_cmp_gt_i32_e32 vcc, s2, v80
	s_and_b64 s[98:99], s[6:7], vcc
	v_mov_b32_e32 v96, 0
	v_mov_b32_e32 v97, 0
	v_mov_b32_e32 v98, 0
	v_mov_b32_e32 v99, 0
	s_and_saveexec_b64 s[100:101], s[98:99]
	v_ashrrev_i32_e32 v81, 31, v80
	v_lshlrev_b64 v[128:129], 12, v[80:81]
	v_lshl_add_u64 v[128:129], v[14:15], 0, v[128:129]
	global_load_dwordx4 v[96:99], v[128:129], off nt
	s_or_b64 exec, exec, s[100:101]
	v_or_b32_e32 v82, s8, v19
	v_cmp_gt_i32_e32 vcc, s2, v82
	s_and_b64 s[98:99], s[6:7], vcc
	v_mov_b32_e32 v100, 0
	v_mov_b32_e32 v101, 0
	v_mov_b32_e32 v102, 0
	v_mov_b32_e32 v103, 0
	s_and_saveexec_b64 s[100:101], s[98:99]
	v_ashrrev_i32_e32 v83, 31, v82
	v_lshlrev_b64 v[130:131], 12, v[82:83]
	v_lshl_add_u64 v[130:131], v[14:15], 0, v[130:131]
	global_load_dwordx4 v[100:103], v[130:131], off nt
	s_or_b64 exec, exec, s[100:101]
	v_or_b32_e32 v84, s8, v20
	v_cmp_gt_i32_e32 vcc, s2, v84
	s_and_b64 s[98:99], s[6:7], vcc
	v_mov_b32_e32 v104, 0
	v_mov_b32_e32 v105, 0
	v_mov_b32_e32 v106, 0
	v_mov_b32_e32 v107, 0
	s_and_saveexec_b64 s[100:101], s[98:99]
	v_ashrrev_i32_e32 v85, 31, v84
	v_lshlrev_b64 v[132:133], 12, v[84:85]
	v_lshl_add_u64 v[132:133], v[14:15], 0, v[132:133]
	global_load_dwordx4 v[104:107], v[132:133], off nt
	s_or_b64 exec, exec, s[100:101]
	v_or_b32_e32 v86, s8, v21
	v_cmp_gt_i32_e32 vcc, s2, v86
	s_and_b64 s[98:99], s[6:7], vcc
	v_mov_b32_e32 v108, 0
	v_mov_b32_e32 v109, 0
	v_mov_b32_e32 v110, 0
	v_mov_b32_e32 v111, 0
	s_and_saveexec_b64 s[100:101], s[98:99]
	v_ashrrev_i32_e32 v87, 31, v86
	v_lshlrev_b64 v[134:135], 12, v[86:87]
	v_lshl_add_u64 v[134:135], v[14:15], 0, v[134:135]
	global_load_dwordx4 v[108:111], v[134:135], off nt
	s_or_b64 exec, exec, s[100:101]
	v_or_b32_e32 v88, s8, v22
	v_cmp_gt_i32_e32 vcc, s2, v88
	s_and_b64 s[98:99], s[6:7], vcc
	v_mov_b32_e32 v112, 0
	v_mov_b32_e32 v113, 0
	v_mov_b32_e32 v114, 0
	v_mov_b32_e32 v115, 0
	s_and_saveexec_b64 s[100:101], s[98:99]
	v_ashrrev_i32_e32 v89, 31, v88
	v_lshlrev_b64 v[136:137], 12, v[88:89]
	v_lshl_add_u64 v[136:137], v[14:15], 0, v[136:137]
	global_load_dwordx4 v[112:115], v[136:137], off nt
	s_or_b64 exec, exec, s[100:101]
	v_or_b32_e32 v90, s8, v23
	v_cmp_gt_i32_e32 vcc, s2, v90
	s_and_b64 s[98:99], s[6:7], vcc
	v_mov_b32_e32 v116, 0
	v_mov_b32_e32 v117, 0
	v_mov_b32_e32 v118, 0
	v_mov_b32_e32 v119, 0
	s_and_saveexec_b64 s[100:101], s[98:99]
	v_ashrrev_i32_e32 v91, 31, v90
	v_lshlrev_b64 v[138:139], 12, v[90:91]
	v_lshl_add_u64 v[138:139], v[14:15], 0, v[138:139]
	global_load_dwordx4 v[116:119], v[138:139], off nt
	s_or_b64 exec, exec, s[100:101]
	v_or_b32_e32 v92, s8, v24
	v_cmp_gt_i32_e32 vcc, s2, v92
	s_and_b64 s[98:99], s[6:7], vcc
	v_mov_b32_e32 v120, 0
	v_mov_b32_e32 v121, 0
	v_mov_b32_e32 v122, 0
	v_mov_b32_e32 v123, 0
	s_and_saveexec_b64 s[100:101], s[98:99]
	v_ashrrev_i32_e32 v93, 31, v92
	v_lshlrev_b64 v[140:141], 12, v[92:93]
	v_lshl_add_u64 v[140:141], v[14:15], 0, v[140:141]
	global_load_dwordx4 v[120:123], v[140:141], off nt
	s_or_b64 exec, exec, s[100:101]
	v_or_b32_e32 v94, s8, v25
	v_cmp_gt_i32_e32 vcc, s2, v94
	s_and_b64 s[98:99], s[6:7], vcc
	v_mov_b32_e32 v124, 0
	v_mov_b32_e32 v125, 0
	v_mov_b32_e32 v126, 0
	v_mov_b32_e32 v127, 0
	s_and_saveexec_b64 s[100:101], s[98:99]
	v_ashrrev_i32_e32 v95, 31, v94
	v_lshlrev_b64 v[142:143], 12, v[94:95]
	v_lshl_add_u64 v[142:143], v[14:15], 0, v[142:143]
	global_load_dwordx4 v[124:127], v[142:143], off nt
	s_or_b64 exec, exec, s[100:101]
	s_waitcnt vmcnt(0)
	ds_write_b128 v27, v[96:99]
	ds_write_b128 v27, v[100:103] offset:1152
	ds_write_b128 v27, v[104:107] offset:2304
	ds_write_b128 v27, v[108:111] offset:3456
	ds_write_b128 v27, v[112:115] offset:4608
	ds_write_b128 v27, v[116:119] offset:5760
	ds_write_b128 v27, v[120:123] offset:6912
	ds_write_b128 v27, v[124:127] offset:8064
	s_branch .Lcv_t6_tr

.LBB0_1470:
.Lcv_t7_tr:
	s_waitcnt lgkmcnt(0)
	v_or_b32_e32 v12, s12, v8
	ds_read2_b32 v[2:3], v26 offset1:36
	s_ashr_i32 s17, s16, 31
	v_ashrrev_i32_e32 v13, 31, v12
	s_waitcnt lgkmcnt(0)
	v_cvt_pk_bf16_f32 v2, v2, v3
	ds_read2_b32 v[4:5], v26 offset0:72 offset1:108
	v_lshl_add_u64 v[14:15], s[16:17], 1, v[10:11]
	v_lshlrev_b64 v[12:13], 11, v[12:13]
	s_waitcnt lgkmcnt(0)
	v_cvt_pk_bf16_f32 v3, v4, v5
	ds_read2_b32 v[4:5], v26 offset0:144 offset1:180
	v_lshl_add_u64 v[12:13], v[14:15], 0, v[12:13]
	s_waitcnt lgkmcnt(0)
	v_cvt_pk_bf16_f32 v4, v4, v5
	ds_read2_b32 v[6:7], v26 offset0:216 offset1:252
	s_waitcnt lgkmcnt(0)
	v_cvt_pk_bf16_f32 v5, v6, v7
	global_store_dwordx4 v[12:13], v[2:5], off
	v_or_b32_e32 v12, s12, v19
	v_ashrrev_i32_e32 v13, 31, v12
	ds_read2_b32 v[6:7], v26 offset0:8 offset1:44
	s_waitcnt lgkmcnt(0)
	v_cvt_pk_bf16_f32 v2, v6, v7
	ds_read2_b32 v[4:5], v26 offset0:80 offset1:116
	v_lshlrev_b64 v[12:13], 11, v[12:13]
	s_waitcnt lgkmcnt(0)
	v_cvt_pk_bf16_f32 v3, v4, v5
	ds_read2_b32 v[4:5], v26 offset0:152 offset1:188
	v_add_u32_e32 v16, 0x200, v26
	v_lshl_add_u64 v[12:13], v[14:15], 0, v[12:13]
	s_waitcnt lgkmcnt(0)
	v_cvt_pk_bf16_f32 v4, v4, v5
	ds_read2_b32 v[6:7], v16 offset0:96 offset1:132
	s_waitcnt lgkmcnt(0)
	v_cvt_pk_bf16_f32 v5, v6, v7
	global_store_dwordx4 v[12:13], v[2:5], off
	v_or_b32_e32 v12, s12, v20
	v_ashrrev_i32_e32 v13, 31, v12
	ds_read2_b32 v[6:7], v26 offset0:16 offset1:52
	s_waitcnt lgkmcnt(0)
	v_cvt_pk_bf16_f32 v2, v6, v7
	ds_read2_b32 v[4:5], v26 offset0:88 offset1:124
	v_lshlrev_b64 v[12:13], 11, v[12:13]
	s_waitcnt lgkmcnt(0)
	v_cvt_pk_bf16_f32 v3, v4, v5
	ds_read2_b32 v[4:5], v26 offset0:160 offset1:196
	v_lshl_add_u64 v[12:13], v[14:15], 0, v[12:13]
	s_waitcnt lgkmcnt(0)
	v_cvt_pk_bf16_f32 v4, v4, v5
	ds_read2_b32 v[6:7], v16 offset0:104 offset1:140
	s_waitcnt lgkmcnt(0)
	v_cvt_pk_bf16_f32 v5, v6, v7
	global_store_dwordx4 v[12:13], v[2:5], off
	v_or_b32_e32 v12, s12, v21
	v_ashrrev_i32_e32 v13, 31, v12
	ds_read2_b32 v[6:7], v26 offset0:24 offset1:60
	s_waitcnt lgkmcnt(0)
	v_cvt_pk_bf16_f32 v2, v6, v7
	ds_read2_b32 v[4:5], v26 offset0:96 offset1:132
	v_lshlrev_b64 v[12:13], 11, v[12:13]
	s_waitcnt lgkmcnt(0)
	v_cvt_pk_bf16_f32 v3, v4, v5
	ds_read2_b32 v[4:5], v26 offset0:168 offset1:204
	v_lshl_add_u64 v[12:13], v[14:15], 0, v[12:13]
	s_waitcnt lgkmcnt(0)
	v_cvt_pk_bf16_f32 v4, v4, v5
	ds_read2_b32 v[6:7], v16 offset0:112 offset1:148
	s_waitcnt lgkmcnt(0)
	v_cvt_pk_bf16_f32 v5, v6, v7
	global_store_dwordx4 v[12:13], v[2:5], off
	s_waitcnt lgkmcnt(0)
	s_add_i32 s12, s1, 0x400
	s_addk_i32 s1, 0x200
	s_cmp_lt_i32 s1, 0
	s_mov_b32 s1, s12
	s_cbranch_scc0 .LBB0_1495
.LBB0_1471:
	s_ashr_i32 s12, s1, 31
	s_lshr_b32 s12, s12, 27
	s_add_i32 s12, s1, s12
	s_and_b32 s13, s12, 0x7ffffe0
	s_sub_i32 s13, s1, s13
	s_lshl_b32 s12, s12, 1
	s_and_b32 s16, s12, 0xffffffc0
	s_lshl_b32 s12, s13, 5
	v_or_b32_e32 v2, s12, v18
	v_or_b32_e32 v6, s16, v8
	v_ashrrev_i32_e32 v3, 31, v2
	v_lshl_add_u64 v[12:13], v[2:3], 2, s[10:11]
	v_mov_b32_e32 v80, v6
	v_cmp_gt_i32_e32 vcc, s2, v80
	s_and_b64 s[98:99], s[6:7], vcc
	v_mov_b32_e32 v96, 0
	v_mov_b32_e32 v97, 0
	v_mov_b32_e32 v98, 0
	v_mov_b32_e32 v99, 0
	v_mov_b32_e32 v160, 1.0
	s_and_saveexec_b64 s[100:101], s[98:99]
	v_ashrrev_i32_e32 v81, 31, v80
	v_lshlrev_b64 v[128:129], 12, v[80:81]
	v_lshl_add_u64 v[128:129], v[12:13], 0, v[128:129]
	global_load_dwordx4 v[96:99], v[128:129], off nt
	s_and_b64 vcc, exec, s[4:5]
	s_cbranch_vccnz .Lcv_t7_ng0
	v_ashrrev_i32_e32 v81, 31, v80
	v_lshl_add_u64 v[144:145], v[80:81], 2, s[8:9]
	global_load_dword v160, v[144:145], off
.Lcv_t7_ng0:
	s_or_b64 exec, exec, s[100:101]
	v_or_b32_e32 v82, s16, v19
	v_cmp_gt_i32_e32 vcc, s2, v82
	s_and_b64 s[98:99], s[6:7], vcc
	v_mov_b32_e32 v100, 0
	v_mov_b32_e32 v101, 0
	v_mov_b32_e32 v102, 0
	v_mov_b32_e32 v103, 0
	v_mov_b32_e32 v161, 1.0
	s_and_saveexec_b64 s[100:101], s[98:99]
	v_ashrrev_i32_e32 v83, 31, v82
	v_lshlrev_b64 v[130:131], 12, v[82:83]
	v_lshl_add_u64 v[130:131], v[12:13], 0, v[130:131]
	global_load_dwordx4 v[100:103], v[130:131], off nt
	s_and_b64 vcc, exec, s[4:5]
	s_cbranch_vccnz .Lcv_t7_ng1
	v_ashrrev_i32_e32 v83, 31, v82
	v_lshl_add_u64 v[146:147], v[82:83], 2, s[8:9]
	global_load_dword v161, v[146:147], off
.Lcv_t7_ng1:
	s_or_b64 exec, exec, s[100:101]
	v_or_b32_e32 v84, s16, v20
	v_cmp_gt_i32_e32 vcc, s2, v84
	s_and_b64 s[98:99], s[6:7], vcc
	v_mov_b32_e32 v104, 0
	v_mov_b32_e32 v105, 0
	v_mov_b32_e32 v106, 0
	v_mov_b32_e32 v107, 0
	v_mov_b32_e32 v162, 1.0
	s_and_saveexec_b64 s[100:101], s[98:99]
	v_ashrrev_i32_e32 v85, 31, v84
	v_lshlrev_b64 v[132:133], 12, v[84:85]
	v_lshl_add_u64 v[132:133], v[12:13], 0, v[132:133]
	global_load_dwordx4 v[104:107], v[132:133], off nt
	s_and_b64 vcc, exec, s[4:5]
	s_cbranch_vccnz .Lcv_t7_ng2
	v_ashrrev_i32_e32 v85, 31, v84
	v_lshl_add_u64 v[148:149], v[84:85], 2, s[8:9]
	global_load_dword v162, v[148:149], off
.Lcv_t7_ng2:
	s_or_b64 exec, exec, s[100:101]
	v_or_b32_e32 v86, s16, v21
	v_cmp_gt_i32_e32 vcc, s2, v86
	s_and_b64 s[98:99], s[6:7], vcc
	v_mov_b32_e32 v108, 0
	v_mov_b32_e32 v109, 0
	v_mov_b32_e32 v110, 0
	v_mov_b32_e32 v111, 0
	v_mov_b32_e32 v163, 1.0
	s_and_saveexec_b64 s[100:101], s[98:99]
	v_ashrrev_i32_e32 v87, 31, v86
	v_lshlrev_b64 v[134:135], 12, v[86:87]
	v_lshl_add_u64 v[134:135], v[12:13], 0, v[134:135]
	global_load_dwordx4 v[108:111], v[134:135], off nt
	s_and_b64 vcc, exec, s[4:5]
	s_cbranch_vccnz .Lcv_t7_ng3
	v_ashrrev_i32_e32 v87, 31, v86
	v_lshl_add_u64 v[150:151], v[86:87], 2, s[8:9]
	global_load_dword v163, v[150:151], off
.Lcv_t7_ng3:
	s_or_b64 exec, exec, s[100:101]
	v_or_b32_e32 v88, s16, v22
	v_cmp_gt_i32_e32 vcc, s2, v88
	s_and_b64 s[98:99], s[6:7], vcc
	v_mov_b32_e32 v112, 0
	v_mov_b32_e32 v113, 0
	v_mov_b32_e32 v114, 0
	v_mov_b32_e32 v115, 0
	v_mov_b32_e32 v164, 1.0
	s_and_saveexec_b64 s[100:101], s[98:99]
	v_ashrrev_i32_e32 v89, 31, v88
	v_lshlrev_b64 v[136:137], 12, v[88:89]
	v_lshl_add_u64 v[136:137], v[12:13], 0, v[136:137]
	global_load_dwordx4 v[112:115], v[136:137], off nt
	s_and_b64 vcc, exec, s[4:5]
	s_cbranch_vccnz .Lcv_t7_ng4
	v_ashrrev_i32_e32 v89, 31, v88
	v_lshl_add_u64 v[152:153], v[88:89], 2, s[8:9]
	global_load_dword v164, v[152:153], off
.Lcv_t7_ng4:
	s_or_b64 exec, exec, s[100:101]
	v_or_b32_e32 v90, s16, v23
	v_cmp_gt_i32_e32 vcc, s2, v90
	s_and_b64 s[98:99], s[6:7], vcc
	v_mov_b32_e32 v116, 0
	v_mov_b32_e32 v117, 0
	v_mov_b32_e32 v118, 0
	v_mov_b32_e32 v119, 0
	v_mov_b32_e32 v165, 1.0
	s_and_saveexec_b64 s[100:101], s[98:99]
	v_ashrrev_i32_e32 v91, 31, v90
	v_lshlrev_b64 v[138:139], 12, v[90:91]
	v_lshl_add_u64 v[138:139], v[12:13], 0, v[138:139]
	global_load_dwordx4 v[116:119], v[138:139], off nt
	s_and_b64 vcc, exec, s[4:5]
	s_cbranch_vccnz .Lcv_t7_ng5
	v_ashrrev_i32_e32 v91, 31, v90
	v_lshl_add_u64 v[154:155], v[90:91], 2, s[8:9]
	global_load_dword v165, v[154:155], off
.Lcv_t7_ng5:
	s_or_b64 exec, exec, s[100:101]
	v_or_b32_e32 v92, s16, v24
	v_cmp_gt_i32_e32 vcc, s2, v92
	s_and_b64 s[98:99], s[6:7], vcc
	v_mov_b32_e32 v120, 0
	v_mov_b32_e32 v121, 0
	v_mov_b32_e32 v122, 0
	v_mov_b32_e32 v123, 0
	v_mov_b32_e32 v166, 1.0
	s_and_saveexec_b64 s[100:101], s[98:99]
	v_ashrrev_i32_e32 v93, 31, v92
	v_lshlrev_b64 v[140:141], 12, v[92:93]
	v_lshl_add_u64 v[140:141], v[12:13], 0, v[140:141]
	global_load_dwordx4 v[120:123], v[140:141], off nt
	s_and_b64 vcc, exec, s[4:5]
	s_cbranch_vccnz .Lcv_t7_ng6
	v_ashrrev_i32_e32 v93, 31, v92
	v_lshl_add_u64 v[156:157], v[92:93], 2, s[8:9]
	global_load_dword v166, v[156:157], off
.Lcv_t7_ng6:
	s_or_b64 exec, exec, s[100:101]
	v_or_b32_e32 v94, s16, v25
	v_cmp_gt_i32_e32 vcc, s2, v94
	s_and_b64 s[98:99], s[6:7], vcc
	v_mov_b32_e32 v124, 0
	v_mov_b32_e32 v125, 0
	v_mov_b32_e32 v126, 0
	v_mov_b32_e32 v127, 0
	v_mov_b32_e32 v167, 1.0
	s_and_saveexec_b64 s[100:101], s[98:99]
	v_ashrrev_i32_e32 v95, 31, v94
	v_lshlrev_b64 v[142:143], 12, v[94:95]
	v_lshl_add_u64 v[142:143], v[12:13], 0, v[142:143]
	global_load_dwordx4 v[124:127], v[142:143], off nt
	s_and_b64 vcc, exec, s[4:5]
	s_cbranch_vccnz .Lcv_t7_ng7
	v_ashrrev_i32_e32 v95, 31, v94
	v_lshl_add_u64 v[158:159], v[94:95], 2, s[8:9]
	global_load_dword v167, v[158:159], off

	.amdhsa_kernel _ZN2mk8mega_fwdENS_4ArgsE
		.amdhsa_group_segment_fixed_size 0
		.amdhsa_private_segment_fixed_size 0
		.amdhsa_kernarg_size 536
		.amdhsa_user_sgpr_count 2
		.amdhsa_user_sgpr_dispatch_ptr 0
		.amdhsa_user_sgpr_queue_ptr 0
		.amdhsa_user_sgpr_kernarg_segment_ptr 1
		.amdhsa_user_sgpr_dispatch_id 0
		.amdhsa_user_sgpr_kernarg_preload_length 0
		.amdhsa_user_sgpr_kernarg_preload_offset 0
		.amdhsa_user_sgpr_private_segment_size 0
		.amdhsa_uses_dynamic_stack 0
		.amdhsa_enable_private_segment 0
		.amdhsa_system_sgpr_workgroup_id_x 1
		.amdhsa_system_sgpr_workgroup_id_y 0
		.amdhsa_system_sgpr_workgroup_id_z 0
		.amdhsa_system_sgpr_workgroup_info 0
		.amdhsa_system_vgpr_workitem_id 0
		.amdhsa_next_free_vgpr 256
		.amdhsa_next_free_sgpr 102
		.amdhsa_accum_offset 256
		.amdhsa_reserve_vcc 1
		.amdhsa_float_round_mode_32 0
		.amdhsa_float_round_mode_16_64 0
		.amdhsa_float_denorm_mode_32 3
		.amdhsa_float_denorm_mode_16_64 3
		.amdhsa_dx10_clamp 1
		.amdhsa_ieee_mode 1
		.amdhsa_fp16_overflow 0
		.amdhsa_tg_split 0
		.amdhsa_exception_fp_ieee_invalid_op 0
		.amdhsa_exception_fp_denorm_src 0
		.amdhsa_exception_fp_ieee_div_zero 0
		.amdhsa_exception_fp_ieee_overflow 0
		.amdhsa_exception_fp_ieee_underflow 0
		.amdhsa_exception_fp_ieee_inexact 0
		.amdhsa_exception_int_div_zero 0
	.end_amdhsa_kernel

amdhsa.kernels:
  - .agpr_count:     0
    .args:
      - .offset:         0
        .size:           280
        .value_kind:     by_value
      - .offset:         280
        .size:           4
        .value_kind:     hidden_block_count_x
      - .offset:         284
        .size:           4
        .value_kind:     hidden_block_count_y
      - .offset:         288
        .size:           4
        .value_kind:     hidden_block_count_z
      - .offset:         292
        .size:           2
        .value_kind:     hidden_group_size_x
      - .offset:         294
        .size:           2
        .value_kind:     hidden_group_size_y
      - .offset:         296
        .size:           2
        .value_kind:     hidden_group_size_z
      - .offset:         298
        .size:           2
        .value_kind:     hidden_remainder_x
      - .offset:         300
        .size:           2
        .value_kind:     hidden_remainder_y
      - .offset:         302
        .size:           2
        .value_kind:     hidden_remainder_z
      - .offset:         320
        .size:           8
        .value_kind:     hidden_global_offset_x
      - .offset:         328
        .size:           8
        .value_kind:     hidden_global_offset_y
      - .offset:         336
        .size:           8
        .value_kind:     hidden_global_offset_z
      - .offset:         344
        .size:           2
        .value_kind:     hidden_grid_dims
      - .offset:         400
        .size:           4
        .value_kind:     hidden_dynamic_lds_size
    .group_segment_fixed_size: 0
    .kernarg_segment_align: 8
    .kernarg_segment_size: 536
    .language:       OpenCL C
    .language_version:
      - 2
      - 0
    .max_flat_workgroup_size: 512
    .name:           _ZN2mk8mega_fwdENS_4ArgsE
    .private_segment_fixed_size: 0
    .sgpr_count:     108
    .sgpr_spill_count: 39
    .symbol:         _ZN2mk8mega_fwdENS_4ArgsE.kd
    .uniform_work_group_size: 1
    .uses_dynamic_stack: false
    .vgpr_count:     256
    .vgpr_spill_count: 0
    .wavefront_size: 64
